# attention: fixed reference max (diag tile) on later tiles with overflow guard + slow-path rerun; EpiResid residual loads batched (counted vmcnt); attention item epilogue sw loads and LDS exchange read
# speedup vs baseline: 1.0171x; 1.0171x over previous
.LBB0_213:
	v_mul_f32_e32 v152, 0xbfb8aa3b, v126
	v_mul_f32_e32 v153, 0xbfb8aa3b, v127
	v_mul_f32_e32 v154, 0xbfb8aa3b, v128
	v_mul_f32_e32 v155, 0xbfb8aa3b, v129
	v_mul_f32_e32 v156, 0xbfb8aa3b, v118
	v_mul_f32_e32 v157, 0xbfb8aa3b, v119
	v_mul_f32_e32 v158, 0xbfb8aa3b, v120
	v_mul_f32_e32 v159, 0xbfb8aa3b, v121
	v_exp_f32_e32 v152, v152
	v_exp_f32_e32 v153, v153
	v_exp_f32_e32 v154, v154
	v_exp_f32_e32 v155, v155
	v_exp_f32_e32 v156, v156
	v_exp_f32_e32 v157, v157
	v_exp_f32_e32 v158, v158
	v_exp_f32_e32 v159, v159
	v_add_f32_e32 v152, 1.0, v152
	v_add_f32_e32 v153, 1.0, v153
	v_add_f32_e32 v154, 1.0, v154
	v_add_f32_e32 v155, 1.0, v155
	v_add_f32_e32 v156, 1.0, v156
	v_add_f32_e32 v157, 1.0, v157
	v_add_f32_e32 v158, 1.0, v158
	v_add_f32_e32 v159, 1.0, v159
	v_rcp_f32_e32 v152, v152
	v_rcp_f32_e32 v153, v153
	v_rcp_f32_e32 v154, v154
	v_rcp_f32_e32 v155, v155
	v_rcp_f32_e32 v156, v156
	v_rcp_f32_e32 v157, v157
	v_rcp_f32_e32 v158, v158
	v_rcp_f32_e32 v159, v159
	v_mul_f32_e32 v152, v126, v152
	v_mul_f32_e32 v153, v127, v153
	v_mul_f32_e32 v154, v128, v154
	v_mul_f32_e32 v155, v129, v155
	v_mul_f32_e32 v156, v118, v156
	v_mul_f32_e32 v157, v119, v157
	v_mul_f32_e32 v158, v120, v158
	v_mul_f32_e32 v159, v121, v159
	v_mul_f32_e32 v152, v152, v122
	v_mul_f32_e32 v153, v153, v123
	v_mul_f32_e32 v154, v154, v124
	v_mul_f32_e32 v155, v155, v125
	v_mul_f32_e32 v156, v156, v114
	v_mul_f32_e32 v157, v157, v115
	v_mul_f32_e32 v158, v158, v116
	v_mul_f32_e32 v159, v159, v117
	v_cvt_pk_bf16_f32 v160, v152, v153
	v_cvt_pk_bf16_f32 v161, v154, v155
	v_cvt_pk_bf16_f32 v162, v156, v157
	v_cvt_pk_bf16_f32 v163, v158, v159
	v_lshl_add_u32 v148, s58, 7, v144
	v_lshl_add_u32 v146, s57, 8, v142
	v_ashrrev_i32_e32 v149, 31, v148
	v_mov_b64_e32 v[140:141], s[0:1]
	v_mad_i64_i32 v[150:151], s[20:21], v146, s62, v[140:141]
	v_readlane_b32 s60, v255, 0
	s_nop 1
	s_andn2_b64 vcc, exec, s[44:45]
	v_readlane_b32 s61, v255, 1
	s_nop 1
	v_lshlrev_b64 v[114:115], 1, v[148:149]
	v_lshl_add_u64 v[120:121], v[150:151], 0, v[114:115]
	global_store_dwordx4 v[120:121], v[160:163], off
	v_mul_f32_e32 v152, 0xbfb8aa3b, v110
	v_mul_f32_e32 v153, 0xbfb8aa3b, v111
	v_mul_f32_e32 v154, 0xbfb8aa3b, v112
	v_mul_f32_e32 v155, 0xbfb8aa3b, v113
	v_mul_f32_e32 v156, 0xbfb8aa3b, v102
	v_mul_f32_e32 v157, 0xbfb8aa3b, v103
	v_mul_f32_e32 v158, 0xbfb8aa3b, v104
	v_mul_f32_e32 v159, 0xbfb8aa3b, v105
	v_exp_f32_e32 v152, v152
	v_exp_f32_e32 v153, v153
	v_exp_f32_e32 v154, v154
	v_exp_f32_e32 v155, v155
	v_exp_f32_e32 v156, v156
	v_exp_f32_e32 v157, v157
	v_exp_f32_e32 v158, v158
	v_exp_f32_e32 v159, v159
	v_add_f32_e32 v152, 1.0, v152
	v_add_f32_e32 v153, 1.0, v153
	v_add_f32_e32 v154, 1.0, v154
	v_add_f32_e32 v155, 1.0, v155
	v_add_f32_e32 v156, 1.0, v156
	v_add_f32_e32 v157, 1.0, v157
	v_add_f32_e32 v158, 1.0, v158
	v_add_f32_e32 v159, 1.0, v159
	v_rcp_f32_e32 v152, v152
	v_rcp_f32_e32 v153, v153
	v_rcp_f32_e32 v154, v154
	v_rcp_f32_e32 v155, v155
	v_rcp_f32_e32 v156, v156
	v_rcp_f32_e32 v157, v157
	v_rcp_f32_e32 v158, v158
	v_rcp_f32_e32 v159, v159
	v_mul_f32_e32 v152, v110, v152
	v_mul_f32_e32 v153, v111, v153
	v_mul_f32_e32 v154, v112, v154
	v_mul_f32_e32 v155, v113, v155
	v_mul_f32_e32 v156, v102, v156
	v_mul_f32_e32 v157, v103, v157
	v_mul_f32_e32 v158, v104, v158
	v_mul_f32_e32 v159, v105, v159
	v_mul_f32_e32 v152, v152, v106
	v_mul_f32_e32 v153, v153, v107
	v_mul_f32_e32 v154, v154, v108
	v_mul_f32_e32 v155, v155, v109
	v_mul_f32_e32 v156, v156, v98
	v_mul_f32_e32 v157, v157, v99
	v_mul_f32_e32 v158, v158, v100
	v_mul_f32_e32 v159, v159, v101
	v_cvt_pk_bf16_f32 v160, v152, v153
	v_cvt_pk_bf16_f32 v161, v154, v155
	v_cvt_pk_bf16_f32 v162, v156, v157
	v_cvt_pk_bf16_f32 v163, v158, v159
	v_or_b32_e32 v116, 16, v146
	v_mad_i64_i32 v[116:117], s[20:21], v116, s62, v[140:141]
	v_lshl_add_u64 v[102:103], v[116:117], 0, v[114:115]
	global_store_dwordx4 v[102:103], v[160:163], off
	v_mul_f32_e32 v152, 0xbfb8aa3b, v94
	v_mul_f32_e32 v153, 0xbfb8aa3b, v95
	v_mul_f32_e32 v154, 0xbfb8aa3b, v96
	v_mul_f32_e32 v155, 0xbfb8aa3b, v97
	v_mul_f32_e32 v156, 0xbfb8aa3b, v86
	v_mul_f32_e32 v157, 0xbfb8aa3b, v87
	v_mul_f32_e32 v158, 0xbfb8aa3b, v88
	v_mul_f32_e32 v159, 0xbfb8aa3b, v89
	v_exp_f32_e32 v152, v152
	v_exp_f32_e32 v153, v153
	v_exp_f32_e32 v154, v154
	v_exp_f32_e32 v155, v155
	v_exp_f32_e32 v156, v156
	v_exp_f32_e32 v157, v157
	v_exp_f32_e32 v158, v158
	v_exp_f32_e32 v159, v159
	v_add_f32_e32 v152, 1.0, v152
	v_add_f32_e32 v153, 1.0, v153
	v_add_f32_e32 v154, 1.0, v154
	v_add_f32_e32 v155, 1.0, v155
	v_add_f32_e32 v156, 1.0, v156
	v_add_f32_e32 v157, 1.0, v157
	v_add_f32_e32 v158, 1.0, v158
	v_add_f32_e32 v159, 1.0, v159
	v_rcp_f32_e32 v152, v152
	v_rcp_f32_e32 v153, v153
	v_rcp_f32_e32 v154, v154
	v_rcp_f32_e32 v155, v155
	v_rcp_f32_e32 v156, v156
	v_rcp_f32_e32 v157, v157
	v_rcp_f32_e32 v158, v158
	v_rcp_f32_e32 v159, v159
	v_mul_f32_e32 v152, v94, v152
	v_mul_f32_e32 v153, v95, v153
	v_mul_f32_e32 v154, v96, v154
	v_mul_f32_e32 v155, v97, v155
	v_mul_f32_e32 v156, v86, v156
	v_mul_f32_e32 v157, v87, v157
	v_mul_f32_e32 v158, v88, v158
	v_mul_f32_e32 v159, v89, v159
	v_mul_f32_e32 v152, v152, v90
	v_mul_f32_e32 v153, v153, v91
	v_mul_f32_e32 v154, v154, v92
	v_mul_f32_e32 v155, v155, v93
	v_mul_f32_e32 v156, v156, v82
	v_mul_f32_e32 v157, v157, v83
	v_mul_f32_e32 v158, v158, v84
	v_mul_f32_e32 v159, v159, v85
	v_cvt_pk_bf16_f32 v160, v152, v153
	v_cvt_pk_bf16_f32 v161, v154, v155
	v_cvt_pk_bf16_f32 v162, v156, v157
	v_cvt_pk_bf16_f32 v163, v158, v159
	v_or_b32_e32 v98, 32, v146
	v_mad_i64_i32 v[98:99], s[20:21], v98, s62, v[140:141]
	v_lshl_add_u64 v[86:87], v[98:99], 0, v[114:115]
	global_store_dwordx4 v[86:87], v[160:163], off
	v_mul_f32_e32 v152, 0xbfb8aa3b, v78
	v_mul_f32_e32 v153, 0xbfb8aa3b, v79
	v_mul_f32_e32 v154, 0xbfb8aa3b, v80
	v_mul_f32_e32 v155, 0xbfb8aa3b, v81
	v_mul_f32_e32 v156, 0xbfb8aa3b, v70
	v_mul_f32_e32 v157, 0xbfb8aa3b, v71
	v_mul_f32_e32 v158, 0xbfb8aa3b, v72
	v_mul_f32_e32 v159, 0xbfb8aa3b, v73
	v_exp_f32_e32 v152, v152
	v_exp_f32_e32 v153, v153
	v_exp_f32_e32 v154, v154
	v_exp_f32_e32 v155, v155
	v_exp_f32_e32 v156, v156
	v_exp_f32_e32 v157, v157
	v_exp_f32_e32 v158, v158
	v_exp_f32_e32 v159, v159
	v_add_f32_e32 v152, 1.0, v152
	v_add_f32_e32 v153, 1.0, v153
	v_add_f32_e32 v154, 1.0, v154
	v_add_f32_e32 v155, 1.0, v155
	v_add_f32_e32 v156, 1.0, v156
	v_add_f32_e32 v157, 1.0, v157
	v_add_f32_e32 v158, 1.0, v158
	v_add_f32_e32 v159, 1.0, v159
	v_rcp_f32_e32 v152, v152
	v_rcp_f32_e32 v153, v153
	v_rcp_f32_e32 v154, v154
	v_rcp_f32_e32 v155, v155
	v_rcp_f32_e32 v156, v156
	v_rcp_f32_e32 v157, v157
	v_rcp_f32_e32 v158, v158
	v_rcp_f32_e32 v159, v159
	v_mul_f32_e32 v152, v78, v152
	v_mul_f32_e32 v153, v79, v153
	v_mul_f32_e32 v154, v80, v154
	v_mul_f32_e32 v155, v81, v155
	v_mul_f32_e32 v156, v70, v156
	v_mul_f32_e32 v157, v71, v157
	v_mul_f32_e32 v158, v72, v158
	v_mul_f32_e32 v159, v73, v159
	v_mul_f32_e32 v152, v152, v74
	v_mul_f32_e32 v153, v153, v75
	v_mul_f32_e32 v154, v154, v76
	v_mul_f32_e32 v155, v155, v77
	v_mul_f32_e32 v156, v156, v66
	v_mul_f32_e32 v157, v157, v67
	v_mul_f32_e32 v158, v158, v68
	v_mul_f32_e32 v159, v159, v69
	v_cvt_pk_bf16_f32 v160, v152, v153
	v_cvt_pk_bf16_f32 v161, v154, v155
	v_cvt_pk_bf16_f32 v162, v156, v157
	v_cvt_pk_bf16_f32 v163, v158, v159
	v_or_b32_e32 v82, 48, v146
	v_mad_i64_i32 v[82:83], s[20:21], v82, s62, v[140:141]
	v_lshl_add_u64 v[70:71], v[82:83], 0, v[114:115]
	global_store_dwordx4 v[70:71], v[160:163], off
	v_mul_f32_e32 v152, 0xbfb8aa3b, v62
	v_mul_f32_e32 v153, 0xbfb8aa3b, v63
	v_mul_f32_e32 v154, 0xbfb8aa3b, v64
	v_mul_f32_e32 v155, 0xbfb8aa3b, v65
	v_mul_f32_e32 v156, 0xbfb8aa3b, v54
	v_mul_f32_e32 v157, 0xbfb8aa3b, v55
	v_mul_f32_e32 v158, 0xbfb8aa3b, v56
	v_mul_f32_e32 v159, 0xbfb8aa3b, v57
	v_exp_f32_e32 v152, v152
	v_exp_f32_e32 v153, v153
	v_exp_f32_e32 v154, v154
	v_exp_f32_e32 v155, v155
	v_exp_f32_e32 v156, v156
	v_exp_f32_e32 v157, v157
	v_exp_f32_e32 v158, v158
	v_exp_f32_e32 v159, v159
	v_add_f32_e32 v152, 1.0, v152
	v_add_f32_e32 v153, 1.0, v153
	v_add_f32_e32 v154, 1.0, v154
	v_add_f32_e32 v155, 1.0, v155
	v_add_f32_e32 v156, 1.0, v156
	v_add_f32_e32 v157, 1.0, v157
	v_add_f32_e32 v158, 1.0, v158
	v_add_f32_e32 v159, 1.0, v159
	v_rcp_f32_e32 v152, v152
	v_rcp_f32_e32 v153, v153
	v_rcp_f32_e32 v154, v154
	v_rcp_f32_e32 v155, v155
	v_rcp_f32_e32 v156, v156
	v_rcp_f32_e32 v157, v157
	v_rcp_f32_e32 v158, v158
	v_rcp_f32_e32 v159, v159
	v_mul_f32_e32 v152, v62, v152
	v_mul_f32_e32 v153, v63, v153
	v_mul_f32_e32 v154, v64, v154
	v_mul_f32_e32 v155, v65, v155
	v_mul_f32_e32 v156, v54, v156
	v_mul_f32_e32 v157, v55, v157
	v_mul_f32_e32 v158, v56, v158
	v_mul_f32_e32 v159, v57, v159
	v_mul_f32_e32 v152, v152, v58
	v_mul_f32_e32 v153, v153, v59
	v_mul_f32_e32 v154, v154, v60
	v_mul_f32_e32 v155, v155, v61
	v_mul_f32_e32 v156, v156, v50
	v_mul_f32_e32 v157, v157, v51
	v_mul_f32_e32 v158, v158, v52
	v_mul_f32_e32 v159, v159, v53
	v_cvt_pk_bf16_f32 v160, v152, v153
	v_cvt_pk_bf16_f32 v161, v154, v155
	v_cvt_pk_bf16_f32 v162, v156, v157
	v_cvt_pk_bf16_f32 v163, v158, v159
	v_add_u32_e32 v66, 0x80, v146
	v_mad_i64_i32 v[66:67], s[20:21], v66, s62, v[140:141]
	v_lshl_add_u64 v[54:55], v[66:67], 0, v[114:115]
	global_store_dwordx4 v[54:55], v[160:163], off
	v_mul_f32_e32 v152, 0xbfb8aa3b, v46
	v_mul_f32_e32 v153, 0xbfb8aa3b, v47
	v_mul_f32_e32 v154, 0xbfb8aa3b, v48
	v_mul_f32_e32 v155, 0xbfb8aa3b, v49
	v_mul_f32_e32 v156, 0xbfb8aa3b, v38
	v_mul_f32_e32 v157, 0xbfb8aa3b, v39
	v_mul_f32_e32 v158, 0xbfb8aa3b, v40
	v_mul_f32_e32 v159, 0xbfb8aa3b, v41
	v_exp_f32_e32 v152, v152
	v_exp_f32_e32 v153, v153
	v_exp_f32_e32 v154, v154
	v_exp_f32_e32 v155, v155
	v_exp_f32_e32 v156, v156
	v_exp_f32_e32 v157, v157
	v_exp_f32_e32 v158, v158
	v_exp_f32_e32 v159, v159
	v_add_f32_e32 v152, 1.0, v152
	v_add_f32_e32 v153, 1.0, v153
	v_add_f32_e32 v154, 1.0, v154
	v_add_f32_e32 v155, 1.0, v155
	v_add_f32_e32 v156, 1.0, v156
	v_add_f32_e32 v157, 1.0, v157
	v_add_f32_e32 v158, 1.0, v158
	v_add_f32_e32 v159, 1.0, v159
	v_rcp_f32_e32 v152, v152
	v_rcp_f32_e32 v153, v153
	v_rcp_f32_e32 v154, v154
	v_rcp_f32_e32 v155, v155
	v_rcp_f32_e32 v156, v156
	v_rcp_f32_e32 v157, v157
	v_rcp_f32_e32 v158, v158
	v_rcp_f32_e32 v159, v159
	v_mul_f32_e32 v152, v46, v152
	v_mul_f32_e32 v153, v47, v153
	v_mul_f32_e32 v154, v48, v154
	v_mul_f32_e32 v155, v49, v155
	v_mul_f32_e32 v156, v38, v156
	v_mul_f32_e32 v157, v39, v157
	v_mul_f32_e32 v158, v40, v158
	v_mul_f32_e32 v159, v41, v159
	v_mul_f32_e32 v152, v152, v42
	v_mul_f32_e32 v153, v153, v43
	v_mul_f32_e32 v154, v154, v44
	v_mul_f32_e32 v155, v155, v45
	v_mul_f32_e32 v156, v156, v34
	v_mul_f32_e32 v157, v157, v35
	v_mul_f32_e32 v158, v158, v36
	v_mul_f32_e32 v159, v159, v37
	v_cvt_pk_bf16_f32 v160, v152, v153
	v_cvt_pk_bf16_f32 v161, v154, v155
	v_cvt_pk_bf16_f32 v162, v156, v157
	v_cvt_pk_bf16_f32 v163, v158, v159
	v_add_u32_e32 v50, 0x90, v146
	v_mad_i64_i32 v[50:51], s[20:21], v50, s62, v[140:141]
	v_lshl_add_u64 v[38:39], v[50:51], 0, v[114:115]
	global_store_dwordx4 v[38:39], v[160:163], off
	v_mul_f32_e32 v152, 0xbfb8aa3b, v30
	v_mul_f32_e32 v153, 0xbfb8aa3b, v31
	v_mul_f32_e32 v154, 0xbfb8aa3b, v32
	v_mul_f32_e32 v155, 0xbfb8aa3b, v33
	v_mul_f32_e32 v156, 0xbfb8aa3b, v22
	v_mul_f32_e32 v157, 0xbfb8aa3b, v23
	v_mul_f32_e32 v158, 0xbfb8aa3b, v24
	v_mul_f32_e32 v159, 0xbfb8aa3b, v25
	v_exp_f32_e32 v152, v152
	v_exp_f32_e32 v153, v153
	v_exp_f32_e32 v154, v154
	v_exp_f32_e32 v155, v155
	v_exp_f32_e32 v156, v156
	v_exp_f32_e32 v157, v157
	v_exp_f32_e32 v158, v158
	v_exp_f32_e32 v159, v159
	v_add_f32_e32 v152, 1.0, v152
	v_add_f32_e32 v153, 1.0, v153
	v_add_f32_e32 v154, 1.0, v154
	v_add_f32_e32 v155, 1.0, v155
	v_add_f32_e32 v156, 1.0, v156
	v_add_f32_e32 v157, 1.0, v157
	v_add_f32_e32 v158, 1.0, v158
	v_add_f32_e32 v159, 1.0, v159
	v_rcp_f32_e32 v152, v152
	v_rcp_f32_e32 v153, v153
	v_rcp_f32_e32 v154, v154
	v_rcp_f32_e32 v155, v155
	v_rcp_f32_e32 v156, v156
	v_rcp_f32_e32 v157, v157
	v_rcp_f32_e32 v158, v158
	v_rcp_f32_e32 v159, v159
	v_mul_f32_e32 v152, v30, v152
	v_mul_f32_e32 v153, v31, v153
	v_mul_f32_e32 v154, v32, v154
	v_mul_f32_e32 v155, v33, v155
	v_mul_f32_e32 v156, v22, v156
	v_mul_f32_e32 v157, v23, v157
	v_mul_f32_e32 v158, v24, v158
	v_mul_f32_e32 v159, v25, v159
	v_mul_f32_e32 v152, v152, v26
	v_mul_f32_e32 v153, v153, v27
	v_mul_f32_e32 v154, v154, v28
	v_mul_f32_e32 v155, v155, v29
	v_mul_f32_e32 v156, v156, v18
	v_mul_f32_e32 v157, v157, v19
	v_mul_f32_e32 v158, v158, v20
	v_mul_f32_e32 v159, v159, v21
	v_cvt_pk_bf16_f32 v160, v152, v153
	v_cvt_pk_bf16_f32 v161, v154, v155
	v_cvt_pk_bf16_f32 v162, v156, v157
	v_cvt_pk_bf16_f32 v163, v158, v159
	v_add_u32_e32 v34, 0xa0, v146
	v_mad_i64_i32 v[34:35], s[20:21], v34, s62, v[140:141]
	v_lshl_add_u64 v[22:23], v[34:35], 0, v[114:115]
	global_store_dwordx4 v[22:23], v[160:163], off
	v_mul_f32_e32 v152, 0xbfb8aa3b, v14
	v_mul_f32_e32 v153, 0xbfb8aa3b, v15
	v_mul_f32_e32 v154, 0xbfb8aa3b, v16
	v_mul_f32_e32 v155, 0xbfb8aa3b, v17
	v_mul_f32_e32 v156, 0xbfb8aa3b, v6
	v_mul_f32_e32 v157, 0xbfb8aa3b, v7
	v_mul_f32_e32 v158, 0xbfb8aa3b, v8
	v_mul_f32_e32 v159, 0xbfb8aa3b, v9
	v_exp_f32_e32 v152, v152
	v_exp_f32_e32 v153, v153
	v_exp_f32_e32 v154, v154
	v_exp_f32_e32 v155, v155
	v_exp_f32_e32 v156, v156
	v_exp_f32_e32 v157, v157
	v_exp_f32_e32 v158, v158
	v_exp_f32_e32 v159, v159
	v_add_f32_e32 v152, 1.0, v152
	v_add_f32_e32 v153, 1.0, v153
	v_add_f32_e32 v154, 1.0, v154
	v_add_f32_e32 v155, 1.0, v155
	v_add_f32_e32 v156, 1.0, v156
	v_add_f32_e32 v157, 1.0, v157
	v_add_f32_e32 v158, 1.0, v158
	v_add_f32_e32 v159, 1.0, v159
	v_rcp_f32_e32 v152, v152
	v_rcp_f32_e32 v153, v153
	v_rcp_f32_e32 v154, v154
	v_rcp_f32_e32 v155, v155
	v_rcp_f32_e32 v156, v156
	v_rcp_f32_e32 v157, v157
	v_rcp_f32_e32 v158, v158
	v_rcp_f32_e32 v159, v159
	v_mul_f32_e32 v152, v14, v152
	v_mul_f32_e32 v153, v15, v153
	v_mul_f32_e32 v154, v16, v154
	v_mul_f32_e32 v155, v17, v155
	v_mul_f32_e32 v156, v6, v156
	v_mul_f32_e32 v157, v7, v157
	v_mul_f32_e32 v158, v8, v158
	v_mul_f32_e32 v159, v9, v159
	v_mul_f32_e32 v152, v152, v10
	v_mul_f32_e32 v153, v153, v11
	v_mul_f32_e32 v154, v154, v12
	v_mul_f32_e32 v155, v155, v13
	v_mul_f32_e32 v156, v156, v2
	v_mul_f32_e32 v157, v157, v3
	v_mul_f32_e32 v158, v158, v4
	v_mul_f32_e32 v159, v159, v5
	v_cvt_pk_bf16_f32 v160, v152, v153
	v_cvt_pk_bf16_f32 v161, v154, v155
	v_cvt_pk_bf16_f32 v162, v156, v157
	v_cvt_pk_bf16_f32 v163, v158, v159
	v_add_u32_e32 v18, 0xb0, v146
	v_mad_i64_i32 v[18:19], s[20:21], v18, s62, v[140:141]
	s_mov_b64 s[20:21], -1
	v_lshl_add_u64 v[6:7], v[18:19], 0, v[114:115]
	global_store_dwordx4 v[6:7], v[160:163], off
	s_cbranch_vccnz .LBB0_206
	s_and_b64 vcc, exec, s[38:39]
	s_cbranch_vccnz .LBB0_205
	s_barrier
	s_branch .LBB0_205

.LBB0_287:
	s_ashr_i32 s18, s61, 5
	s_mul_hi_i32 s19, s18, 0x9000
	s_mul_i32 s18, s18, 0x9000
	s_add_u32 s18, s44, s18
	s_addc_u32 s19, s45, s19
	v_lshl_add_u32 v200, s64, 8, v146
	v_ashrrev_i32_e32 v201, 31, v200
	v_lshlrev_b64 v[200:201], 2, v[200:201]
	v_lshl_add_u64 v[202:203], s[18:19], 0, v[200:201]
	s_and_b64 vcc, exec, s[46:47]
	s_mov_b64 s[18:19], -1
	global_load_dwordx4 v[136:139], v[202:203], off
	global_load_dwordx4 v[140:143], v[202:203], off offset:64
	global_load_dwordx4 v[148:151], v[202:203], off offset:512
	global_load_dwordx4 v[152:155], v[202:203], off offset:576
	v_lshl_add_u32 v194, s61, 8, v144
	v_mov_b32_e32 v196, v194
	v_ashrrev_i32_e32 v197, 31, v196
	v_lshlrev_b64 v[196:197], 12, v[196:197]
	v_lshl_add_u64 v[196:197], v[196:197], 0, v[200:201]
	v_lshl_add_u64 v[198:199], s[0:1], 0, v[196:197]
	global_load_dwordx4 v[156:159], v[198:199], off
	global_load_dwordx4 v[160:163], v[198:199], off offset:64
	global_load_dwordx4 v[164:167], v[198:199], off offset:512
	global_load_dwordx4 v[168:171], v[198:199], off offset:576
	v_add_u32_e32 v196, 16, v194
	v_ashrrev_i32_e32 v197, 31, v196
	v_lshlrev_b64 v[196:197], 12, v[196:197]
	v_lshl_add_u64 v[196:197], v[196:197], 0, v[200:201]
	v_lshl_add_u64 v[198:199], s[0:1], 0, v[196:197]
	global_load_dwordx4 v[172:175], v[198:199], off
	global_load_dwordx4 v[176:179], v[198:199], off offset:64
	global_load_dwordx4 v[180:183], v[198:199], off offset:512
	global_load_dwordx4 v[184:187], v[198:199], off offset:576
	s_waitcnt vmcnt(4)
	v_pk_mul_f32 v[136:137], v[136:137], 0.5 op_sel_hi:[1,0]
	v_pk_mul_f32 v[138:139], v[138:139], 0.5 op_sel_hi:[1,0]
	v_pk_mul_f32 v[140:141], v[140:141], 0.5 op_sel_hi:[1,0]
	v_pk_mul_f32 v[142:143], v[142:143], 0.5 op_sel_hi:[1,0]
	v_pk_mul_f32 v[148:149], v[148:149], 0.5 op_sel_hi:[1,0]
	v_pk_mul_f32 v[150:151], v[150:151], 0.5 op_sel_hi:[1,0]
	v_pk_mul_f32 v[152:153], v[152:153], 0.5 op_sel_hi:[1,0]
	v_pk_mul_f32 v[154:155], v[154:155], 0.5 op_sel_hi:[1,0]
	v_pk_fma_f32 v[126:127], v[126:127], v[136:137], v[156:157]
	v_pk_fma_f32 v[128:129], v[128:129], v[138:139], v[158:159]
	v_pk_fma_f32 v[122:123], v[122:123], v[140:141], v[160:161]
	v_pk_fma_f32 v[124:125], v[124:125], v[142:143], v[162:163]
	v_pk_fma_f32 v[118:119], v[118:119], v[148:149], v[164:165]
	v_pk_fma_f32 v[120:121], v[120:121], v[150:151], v[166:167]
	v_pk_fma_f32 v[106:107], v[106:107], v[152:153], v[168:169]
	v_pk_fma_f32 v[108:109], v[108:109], v[154:155], v[170:171]
	v_mov_b32_e32 v196, v194
	v_ashrrev_i32_e32 v197, 31, v196
	v_lshlrev_b64 v[196:197], 12, v[196:197]
	v_lshl_add_u64 v[196:197], v[196:197], 0, v[200:201]
	v_lshl_add_u64 v[192:193], s[56:57], 0, v[196:197]
	global_store_dwordx4 v[192:193], v[126:129], off
	global_store_dwordx4 v[192:193], v[122:125], off offset:64
	global_store_dwordx4 v[192:193], v[118:121], off offset:512
	global_store_dwordx4 v[192:193], v[106:109], off offset:576
	s_nop 1
	v_add_u32_e32 v196, 32, v194
	v_ashrrev_i32_e32 v197, 31, v196
	v_lshlrev_b64 v[196:197], 12, v[196:197]
	v_lshl_add_u64 v[196:197], v[196:197], 0, v[200:201]
	v_lshl_add_u64 v[198:199], s[0:1], 0, v[196:197]
	global_load_dwordx4 v[188:191], v[198:199], off
	global_load_dwordx4 v[156:159], v[198:199], off offset:64
	global_load_dwordx4 v[160:163], v[198:199], off offset:512
	global_load_dwordx4 v[164:167], v[198:199], off offset:576
	v_add_u32_e32 v196, 48, v194
	v_ashrrev_i32_e32 v197, 31, v196
	v_lshlrev_b64 v[196:197], 12, v[196:197]
	v_lshl_add_u64 v[196:197], v[196:197], 0, v[200:201]
	v_lshl_add_u64 v[198:199], s[0:1], 0, v[196:197]
	global_load_dwordx4 v[168:171], v[198:199], off
	global_load_dwordx4 v[126:129], v[198:199], off offset:64
	global_load_dwordx4 v[122:125], v[198:199], off offset:512
	global_load_dwordx4 v[118:121], v[198:199], off offset:576
	s_waitcnt vmcnt(12)
	v_pk_fma_f32 v[114:115], v[114:115], v[136:137], v[172:173]
	v_pk_fma_f32 v[116:117], v[116:117], v[138:139], v[174:175]
	v_pk_fma_f32 v[110:111], v[110:111], v[140:141], v[176:177]
	v_pk_fma_f32 v[112:113], v[112:113], v[142:143], v[178:179]
	v_pk_fma_f32 v[102:103], v[102:103], v[148:149], v[180:181]
	v_pk_fma_f32 v[104:105], v[104:105], v[150:151], v[182:183]
	v_pk_fma_f32 v[90:91], v[90:91], v[152:153], v[184:185]
	v_pk_fma_f32 v[92:93], v[92:93], v[154:155], v[186:187]
	v_add_u32_e32 v196, 16, v194
	v_ashrrev_i32_e32 v197, 31, v196
	v_lshlrev_b64 v[196:197], 12, v[196:197]
	v_lshl_add_u64 v[196:197], v[196:197], 0, v[200:201]
	v_lshl_add_u64 v[192:193], s[56:57], 0, v[196:197]
	global_store_dwordx4 v[192:193], v[114:117], off
	global_store_dwordx4 v[192:193], v[110:113], off offset:64
	global_store_dwordx4 v[192:193], v[102:105], off offset:512
	global_store_dwordx4 v[192:193], v[90:93], off offset:576
	s_nop 1
	v_add_u32_e32 v196, 0x80, v194
	v_ashrrev_i32_e32 v197, 31, v196
	v_lshlrev_b64 v[196:197], 12, v[196:197]
	v_lshl_add_u64 v[196:197], v[196:197], 0, v[200:201]
	v_lshl_add_u64 v[198:199], s[0:1], 0, v[196:197]
	global_load_dwordx4 v[106:109], v[198:199], off
	global_load_dwordx4 v[172:175], v[198:199], off offset:64
	global_load_dwordx4 v[176:179], v[198:199], off offset:512
	global_load_dwordx4 v[180:183], v[198:199], off offset:576
	v_add_u32_e32 v196, 0x90, v194
	v_ashrrev_i32_e32 v197, 31, v196
	v_lshlrev_b64 v[196:197], 12, v[196:197]
	v_lshl_add_u64 v[196:197], v[196:197], 0, v[200:201]
	v_lshl_add_u64 v[198:199], s[0:1], 0, v[196:197]
	global_load_dwordx4 v[184:187], v[198:199], off
	global_load_dwordx4 v[114:117], v[198:199], off offset:64
	global_load_dwordx4 v[110:113], v[198:199], off offset:512
	global_load_dwordx4 v[102:105], v[198:199], off offset:576
	s_waitcnt vmcnt(16)
	v_pk_fma_f32 v[98:99], v[98:99], v[136:137], v[188:189]
	v_pk_fma_f32 v[100:101], v[100:101], v[138:139], v[190:191]
	v_pk_fma_f32 v[94:95], v[94:95], v[140:141], v[156:157]
	v_pk_fma_f32 v[96:97], v[96:97], v[142:143], v[158:159]
	v_pk_fma_f32 v[86:87], v[86:87], v[148:149], v[160:161]
	v_pk_fma_f32 v[88:89], v[88:89], v[150:151], v[162:163]
	v_pk_fma_f32 v[74:75], v[74:75], v[152:153], v[164:165]
	v_pk_fma_f32 v[76:77], v[76:77], v[154:155], v[166:167]
	v_add_u32_e32 v196, 32, v194
	v_ashrrev_i32_e32 v197, 31, v196
	v_lshlrev_b64 v[196:197], 12, v[196:197]
	v_lshl_add_u64 v[196:197], v[196:197], 0, v[200:201]
	v_lshl_add_u64 v[192:193], s[56:57], 0, v[196:197]
	global_store_dwordx4 v[192:193], v[98:101], off
	global_store_dwordx4 v[192:193], v[94:97], off offset:64
	global_store_dwordx4 v[192:193], v[86:89], off offset:512
	global_store_dwordx4 v[192:193], v[74:77], off offset:576
	s_nop 1
	v_add_u32_e32 v196, 0xa0, v194
	v_ashrrev_i32_e32 v197, 31, v196
	v_lshlrev_b64 v[196:197], 12, v[196:197]
	v_lshl_add_u64 v[196:197], v[196:197], 0, v[200:201]
	v_lshl_add_u64 v[198:199], s[0:1], 0, v[196:197]
	global_load_dwordx4 v[90:93], v[198:199], off
	global_load_dwordx4 v[188:191], v[198:199], off offset:64
	global_load_dwordx4 v[156:159], v[198:199], off offset:512
	global_load_dwordx4 v[160:163], v[198:199], off offset:576
	v_add_u32_e32 v196, 0xb0, v194
	v_ashrrev_i32_e32 v197, 31, v196
	v_lshlrev_b64 v[196:197], 12, v[196:197]
	v_lshl_add_u64 v[196:197], v[196:197], 0, v[200:201]
	v_lshl_add_u64 v[198:199], s[0:1], 0, v[196:197]
	global_load_dwordx4 v[164:167], v[198:199], off
	global_load_dwordx4 v[98:101], v[198:199], off offset:64
	global_load_dwordx4 v[94:97], v[198:199], off offset:512
	global_load_dwordx4 v[86:89], v[198:199], off offset:576
	s_waitcnt vmcnt(24)
	v_pk_fma_f32 v[82:83], v[82:83], v[136:137], v[168:169]
	v_pk_fma_f32 v[84:85], v[84:85], v[138:139], v[170:171]
	v_pk_fma_f32 v[78:79], v[78:79], v[140:141], v[126:127]
	v_pk_fma_f32 v[80:81], v[80:81], v[142:143], v[128:129]
	v_pk_fma_f32 v[70:71], v[70:71], v[148:149], v[122:123]
	v_pk_fma_f32 v[72:73], v[72:73], v[150:151], v[124:125]
	v_pk_fma_f32 v[66:67], v[66:67], v[152:153], v[118:119]
	v_pk_fma_f32 v[68:69], v[68:69], v[154:155], v[120:121]
	v_add_u32_e32 v196, 48, v194
	v_ashrrev_i32_e32 v197, 31, v196
	v_lshlrev_b64 v[196:197], 12, v[196:197]
	v_lshl_add_u64 v[196:197], v[196:197], 0, v[200:201]
	v_lshl_add_u64 v[192:193], s[56:57], 0, v[196:197]
	global_store_dwordx4 v[192:193], v[82:85], off
	global_store_dwordx4 v[192:193], v[78:81], off offset:64
	global_store_dwordx4 v[192:193], v[70:73], off offset:512
	global_store_dwordx4 v[192:193], v[66:69], off offset:576
	s_waitcnt vmcnt(20)
	v_pk_fma_f32 v[62:63], v[62:63], v[136:137], v[106:107]
	v_pk_fma_f32 v[64:65], v[64:65], v[138:139], v[108:109]
	v_pk_fma_f32 v[58:59], v[58:59], v[140:141], v[172:173]
	v_pk_fma_f32 v[60:61], v[60:61], v[142:143], v[174:175]
	v_pk_fma_f32 v[54:55], v[54:55], v[148:149], v[176:177]
	v_pk_fma_f32 v[56:57], v[56:57], v[150:151], v[178:179]
	v_pk_fma_f32 v[42:43], v[42:43], v[152:153], v[180:181]
	v_pk_fma_f32 v[44:45], v[44:45], v[154:155], v[182:183]
	v_add_u32_e32 v196, 0x80, v194
	v_ashrrev_i32_e32 v197, 31, v196
	v_lshlrev_b64 v[196:197], 12, v[196:197]
	v_lshl_add_u64 v[196:197], v[196:197], 0, v[200:201]
	v_lshl_add_u64 v[192:193], s[56:57], 0, v[196:197]
	global_store_dwordx4 v[192:193], v[62:65], off
	global_store_dwordx4 v[192:193], v[58:61], off offset:64
	global_store_dwordx4 v[192:193], v[54:57], off offset:512
	global_store_dwordx4 v[192:193], v[42:45], off offset:576
	s_waitcnt vmcnt(20)
	v_pk_fma_f32 v[50:51], v[50:51], v[136:137], v[184:185]
	v_pk_fma_f32 v[52:53], v[52:53], v[138:139], v[186:187]
	v_pk_fma_f32 v[46:47], v[46:47], v[140:141], v[114:115]
	v_pk_fma_f32 v[48:49], v[48:49], v[142:143], v[116:117]
	v_pk_fma_f32 v[38:39], v[38:39], v[148:149], v[110:111]
	v_pk_fma_f32 v[40:41], v[40:41], v[150:151], v[112:113]
	v_pk_fma_f32 v[26:27], v[26:27], v[152:153], v[102:103]
	v_pk_fma_f32 v[28:29], v[28:29], v[154:155], v[104:105]
	v_add_u32_e32 v196, 0x90, v194
	v_ashrrev_i32_e32 v197, 31, v196
	v_lshlrev_b64 v[196:197], 12, v[196:197]
	v_lshl_add_u64 v[196:197], v[196:197], 0, v[200:201]
	v_lshl_add_u64 v[192:193], s[56:57], 0, v[196:197]
	global_store_dwordx4 v[192:193], v[50:53], off
	global_store_dwordx4 v[192:193], v[46:49], off offset:64
	global_store_dwordx4 v[192:193], v[38:41], off offset:512
	global_store_dwordx4 v[192:193], v[26:29], off offset:576
	s_waitcnt vmcnt(16)
	v_pk_fma_f32 v[34:35], v[34:35], v[136:137], v[90:91]
	v_pk_fma_f32 v[36:37], v[36:37], v[138:139], v[92:93]
	v_pk_fma_f32 v[30:31], v[30:31], v[140:141], v[188:189]
	v_pk_fma_f32 v[32:33], v[32:33], v[142:143], v[190:191]
	v_pk_fma_f32 v[22:23], v[22:23], v[148:149], v[156:157]
	v_pk_fma_f32 v[24:25], v[24:25], v[150:151], v[158:159]
	v_pk_fma_f32 v[10:11], v[10:11], v[152:153], v[160:161]
	v_pk_fma_f32 v[12:13], v[12:13], v[154:155], v[162:163]
	v_add_u32_e32 v196, 0xa0, v194
	v_ashrrev_i32_e32 v197, 31, v196
	v_lshlrev_b64 v[196:197], 12, v[196:197]
	v_lshl_add_u64 v[196:197], v[196:197], 0, v[200:201]
	v_lshl_add_u64 v[192:193], s[56:57], 0, v[196:197]
	global_store_dwordx4 v[192:193], v[34:37], off
	global_store_dwordx4 v[192:193], v[30:33], off offset:64
	global_store_dwordx4 v[192:193], v[22:25], off offset:512
	global_store_dwordx4 v[192:193], v[10:13], off offset:576
	s_waitcnt vmcnt(16)
	v_pk_fma_f32 v[18:19], v[18:19], v[136:137], v[164:165]
	v_pk_fma_f32 v[20:21], v[20:21], v[138:139], v[166:167]
	v_pk_fma_f32 v[14:15], v[14:15], v[140:141], v[98:99]
	v_pk_fma_f32 v[16:17], v[16:17], v[142:143], v[100:101]
	v_pk_fma_f32 v[6:7], v[6:7], v[148:149], v[94:95]
	v_pk_fma_f32 v[8:9], v[8:9], v[150:151], v[96:97]
	v_pk_fma_f32 v[2:3], v[2:3], v[152:153], v[86:87]
	v_pk_fma_f32 v[4:5], v[4:5], v[154:155], v[88:89]
	v_add_u32_e32 v196, 0xb0, v194
	v_ashrrev_i32_e32 v197, 31, v196
	v_lshlrev_b64 v[196:197], 12, v[196:197]
	v_lshl_add_u64 v[196:197], v[196:197], 0, v[200:201]
	v_lshl_add_u64 v[192:193], s[56:57], 0, v[196:197]
	global_store_dwordx4 v[192:193], v[18:21], off
	global_store_dwordx4 v[192:193], v[14:17], off offset:64
	global_store_dwordx4 v[192:193], v[6:9], off offset:512
	global_store_dwordx4 v[192:193], v[2:5], off offset:576
	s_cbranch_vccnz .LBB0_276
	s_and_b64 vcc, exec, s[38:39]
	s_cbranch_vccnz .LBB0_275
	s_barrier
	s_branch .LBB0_275

.LBB0_491:
	s_nop 0
	v_lshl_add_u32 v2, s40, 6, v180
	v_ashrrev_i32_e32 v3, 31, v2
	v_readlane_b32 s44, v255, 18
	v_lshlrev_b64 v[2:3], 2, v[2:3]
	v_readlane_b32 s46, v255, 20
	v_readlane_b32 s47, v255, 21
	v_readlane_b32 s48, v255, 22
	v_readlane_b32 s49, v255, 23
	v_lshl_add_u64 v[4:5], s[46:47], 0, v[2:3]
	v_readlane_b32 s20, v255, 26
	v_readlane_b32 s50, v255, 24
	v_readlane_b32 s51, v255, 25
	global_load_dword v0, v[4:5], off
	v_lshl_add_u64 v[4:5], s[48:49], 0, v[2:3]
	v_readlane_b32 s21, v255, 27
	global_load_dword v6, v[4:5], off
	v_lshl_add_u64 v[4:5], s[50:51], 0, v[2:3]
	v_lshl_add_u64 v[2:3], s[20:21], 0, v[2:3]
	global_load_dword v4, v[4:5], off
	v_cvt_f32_u32_e32 v5, s40
	global_load_dword v2, v[2:3], off
	v_lshlrev_b32_e32 v3, 2, v180
	v_xor_b32_e32 v8, 4, v3
	v_xor_b32_e32 v9, 8, v3
	v_sub_u32_e32 v7, 0, v180
	v_mul_f32_e32 v5, 0xbe99999a, v5
	v_cmp_eq_u32_e64 s[46:47], s3, v7
	v_mul_f32_e32 v7, 0x3fb8aa3b, v5
	v_xor_b32_e32 v10, 16, v3
	s_mov_b32 s18, 0x3fb8aa3b
	v_rndne_f32_e32 v15, v7
	v_xor_b32_e32 v11, 32, v3
	s_lshl_b32 s70, s40, 3
	v_xor_b32_e32 v12, 64, v3
	s_lshl_b64 s[10:11], s[70:71], 2
	s_add_u32 s35, s0, s10
	s_addc_u32 s36, s1, s11
	s_lshl_b64 s[14:15], s[40:41], 9
	s_add_u32 s10, s0, 0x24000000
	s_addc_u32 s11, s1, 0
	v_xor_b32_e32 v3, 0x80, v3
	s_add_u32 s40, s0, 0x2c000000
	s_addc_u32 s41, s1, 0
	s_add_u32 s42, s0, 0x34000000
	v_readlane_b32 s22, v255, 28
	s_addc_u32 s43, s1, 0
	s_add_u32 s0, s22, s14
	s_mov_b32 s14, 0xc2ce8ed0
	v_cmp_ngt_f32_e32 vcc, s14, v5
	s_mov_b32 s19, 0x42b17218
	v_readlane_b32 s23, v255, 29
	s_mov_b32 s34, 0
	s_getreg_b32 s37, hwreg(HW_REG_XCC_ID, 0, 4)
	v_readlane_b32 s45, v255, 19
	s_waitcnt vmcnt(2)
	v_mul_f32_e32 v13, v0, v6
	ds_bpermute_b32 v13, v8, v13
	s_waitcnt vmcnt(0)
	v_mul_f32_e32 v14, v4, v2
	ds_bpermute_b32 v8, v8, v14
	s_waitcnt lgkmcnt(1)
	v_fmac_f32_e32 v13, v0, v6
	ds_bpermute_b32 v0, v9, v13
	v_fma_f32 v14, v5, s18, -v7
	v_fmac_f32_e32 v14, 0x32a5705f, v5
	s_waitcnt lgkmcnt(1)
	v_fmac_f32_e32 v8, v4, v2
	ds_bpermute_b32 v2, v9, v8
	s_waitcnt lgkmcnt(1)
	v_add_f32_e32 v0, v13, v0
	v_sub_f32_e32 v4, v7, v15
	ds_bpermute_b32 v7, v10, v0
	v_add_f32_e32 v4, v4, v14
	s_waitcnt lgkmcnt(1)
	v_add_f32_e32 v2, v8, v2
	ds_bpermute_b32 v8, v10, v2
	v_cvt_i32_f32_e32 v6, v15
	s_waitcnt lgkmcnt(1)
	v_add_f32_e32 v0, v0, v7
	ds_bpermute_b32 v7, v11, v0
	v_exp_f32_e32 v4, v4
	s_waitcnt lgkmcnt(1)
	v_add_f32_e32 v2, v2, v8
	ds_bpermute_b32 v8, v11, v2
	v_mov_b32_e32 v9, 0x7f800000
	s_waitcnt lgkmcnt(1)
	v_add_f32_e32 v0, v0, v7
	ds_bpermute_b32 v7, v12, v0
	v_ldexp_f32 v4, v4, v6
	s_waitcnt lgkmcnt(1)
	v_add_f32_e32 v2, v2, v8
	ds_bpermute_b32 v8, v12, v2
	v_cndmask_b32_e32 v4, 0, v4, vcc
	s_waitcnt lgkmcnt(1)
	v_add_f32_e32 v0, v0, v7
	ds_bpermute_b32 v6, v3, v0
	v_cmp_nlt_f32_e32 vcc, s19, v5
	s_waitcnt lgkmcnt(1)
	v_add_f32_e32 v2, v2, v8
	ds_bpermute_b32 v3, v3, v2
	v_cndmask_b32_e32 v4, v9, v4, vcc
	s_waitcnt lgkmcnt(1)
	v_add_f32_e32 v0, v0, v6
	v_readfirstlane_b32 s1, v4
	v_cmp_ngt_f32_e32 vcc, s14, v0
	s_waitcnt lgkmcnt(0)
	v_add_f32_e32 v2, v2, v3
	v_mul_f32_e32 v3, 0x3fb8aa3b, v0
	v_mul_f32_e32 v4, 0x3fb8aa3b, v2
	v_fma_f32 v5, v0, s18, -v3
	v_rndne_f32_e32 v6, v3
	v_fma_f32 v7, v2, s18, -v4
	v_rndne_f32_e32 v8, v4
	v_fmac_f32_e32 v5, 0x32a5705f, v0
	v_sub_f32_e32 v3, v3, v6
	v_fmac_f32_e32 v7, 0x32a5705f, v2
	v_sub_f32_e32 v4, v4, v8
	v_add_f32_e32 v3, v3, v5
	v_cvt_i32_f32_e32 v6, v6
	v_add_f32_e32 v4, v4, v7
	v_exp_f32_e32 v3, v3
	v_cvt_i32_f32_e32 v8, v8
	v_exp_f32_e32 v4, v4
	v_mov_b32_e32 v5, 0x3f4ccccd
	v_ldexp_f32 v3, v3, v6
	v_cndmask_b32_e32 v3, 0, v3, vcc
	v_ldexp_f32 v4, v4, v8
	v_cmp_ngt_f32_e32 vcc, s14, v2
	v_mov_b32_e32 v7, 0xbf19999a
	v_fma_f32 v5, s1, v7, v5
	v_cndmask_b32_e32 v4, 0, v4, vcc
	v_cmp_nlt_f32_e32 vcc, s19, v0
	v_sub_f32_e32 v141, 1.0, v5
	s_addc_u32 s1, s23, s15
	v_cndmask_b32_e32 v0, v9, v3, vcc
	v_cmp_nlt_f32_e32 vcc, s19, v2
	s_nop 1
	v_cndmask_b32_e32 v2, v9, v4, vcc
	v_sub_f32_e32 v0, v0, v2
	v_add_f32_e32 v0, v5, v0
	s_nop 0
	v_readfirstlane_b32 s14, v0
	s_mov_b32 s15, s14
	s_mov_b32 s100, 0
	v_mov_b32_e32 v142, s85
	v_mov_b32_e32 v143, 0
	ds_write_b32 v142, v143 offset:32
	s_branch .LBB0_493

.LBB0_496:
	s_mov_b32 s100, 0
	s_and_saveexec_b64 s[20:21], s[46:47]
	s_cbranch_execz .LBB0_500
	s_mov_b64 s[24:25], exec
	v_mbcnt_lo_u32_b32 v0, s24, 0
	v_mbcnt_hi_u32_b32 v0, s25, v0
	v_cmp_eq_u32_e32 vcc, 0, v0
	s_and_saveexec_b64 s[22:23], vcc
	s_cbranch_execz .LBB0_499
	s_bcnt1_i32_b64 s24, s[24:25]
	v_mov_b32_e32 v2, s24
	global_atomic_add v2, v1, v2, s[18:19] sc0

.Lattn_item_start:
	s_lshr_b32 s20, s22, 6
	s_sub_i32 s23, 7, s20
	s_andn2_b32 s20, 63, s22
	s_lshl_b32 s22, s20, 7
	s_lshl_b32 s70, s20, 1
	s_add_i32 s20, s23, 1
	v_cvt_f32_i32_e32 v0, s20
	s_mov_b32 s20, 0x42fc0000
	v_mov_b32_e32 v5, v206
	v_cmp_lt_f32_e32 vcc, s20, v0
	s_and_b64 s[20:21], vcc, exec
	s_cselect_b32 s20, 0xffffffc0, 0
	v_cndmask_b32_e32 v2, 0, v237, vcc
	v_sub_f32_e32 v0, v2, v0
	v_exp_f32_e32 v0, v0
	v_and_b32_e32 v4, 31, v5
	v_ashrrev_i32_e32 v6, 5, v5
	s_lshl_b32 s24, s13, 1
	v_ldexp_f32 v0, v0, s20
	s_or_b32 s20, s22, s45
	v_readfirstlane_b32 s48, v0
	v_or_b32_e32 v0, s20, v4
	s_lshl_b32 s20, s23, 7
	v_lshlrev_b32_e32 v0, 11, v0
	s_ashr_i32 s21, s20, 31
	v_lshl_add_u64 v[2:3], s[10:11], 0, v[0:1]
	s_lshl_b64 s[20:21], s[20:21], 1
	v_lshl_add_u64 v[216:217], v[2:3], 0, s[20:21]
	s_mov_b32 s25, s71
	v_lshlrev_b32_e32 v2, 3, v6
	v_mov_b32_e32 v0, 0x3fb8aa3b
	v_lshl_add_u64 v[8:9], v[216:217], 0, s[24:25]
	v_ashrrev_i32_e32 v3, 31, v2
	v_mul_f32_e32 v226, s48, v0
	v_lshl_add_u64 v[8:9], v[2:3], 1, v[8:9]
	v_div_scale_f32 v7, s[48:49], v226, v226, s86
	global_load_dwordx4 v[174:177], v[8:9], off
	global_load_dwordx4 v[178:181], v[8:9], off offset:32
	global_load_dwordx4 v[182:185], v[8:9], off offset:64
	global_load_dwordx4 v[186:189], v[8:9], off offset:96
	v_rcp_f32_e32 v8, v7
	s_sub_i32 s23, s22, 63
	v_cvt_f32_i32_e32 v0, s23
	s_or_b32 s22, s22, s44
	v_fma_f32 v9, -v7, v8, 1.0
	v_fmac_f32_e32 v8, v9, v8
	v_div_scale_f32 v9, vcc, s86, v226, s86
	v_mul_f32_e32 v10, v9, v8
	v_fma_f32 v11, -v7, v10, v9
	v_fmac_f32_e32 v10, v11, v8
	v_fma_f32 v7, -v7, v10, v9
	v_div_fmas_f32 v7, v7, v8, v10
	v_div_fixup_f32 v7, v7, v226, s86
	v_add_f32_e32 v0, v0, v7
	s_or_b32 s22, s22, 64
	v_add_u32_e32 v3, s3, v5
	v_mul_f32_e32 v0, 0x3c800000, v0
	s_add_u32 s48, s40, s20
	v_ceil_f32_e32 v0, v0
	s_addc_u32 s49, s41, s21
	v_ashrrev_i32_e32 v232, 4, v3
	v_cvt_i32_f32_e32 v7, v0
	s_mov_b32 s23, s71
	v_lshlrev_b32_e32 v0, 4, v5
	s_add_u32 s20, s42, s20
	v_ashrrev_i32_e32 v233, 31, v232
	v_and_b32_e32 v0, 0xf0, v0
	s_addc_u32 s21, s43, s21
	v_lshl_add_u64 v[8:9], v[232:233], 0, s[22:23]
	v_add_u32_e32 v3, 0x200, v3
	v_lshl_add_u64 v[228:229], s[48:49], 0, v[0:1]
	v_lshl_add_u64 v[230:231], s[20:21], 0, v[0:1]
	v_lshlrev_b64 v[8:9], 11, v[8:9]
	v_ashrrev_i32_e32 v234, 4, v3
	v_lshl_add_u64 v[10:11], v[228:229], 0, v[8:9]
	v_lshl_add_u64 v[8:9], v[230:231], 0, v[8:9]
	v_ashrrev_i32_e32 v235, 31, v234
	global_load_dwordx4 v[190:193], v[10:11], off
	global_load_dwordx4 v[194:197], v[8:9], off
	v_lshl_add_u64 v[8:9], v[234:235], 0, s[22:23]
	v_lshlrev_b64 v[8:9], 11, v[8:9]
	v_lshl_add_u64 v[10:11], v[228:229], 0, v[8:9]
	global_load_dwordx4 v[198:201], v[10:11], off
	v_lshl_add_u64 v[8:9], v[230:231], 0, v[8:9]
	global_load_dwordx4 v[202:205], v[8:9], off
	v_add_u32_e32 v221, 0, v0
	v_mul_lo_u32 v223, v232, s83
	v_add_u32_e32 v0, v221, v223
	v_mul_lo_u32 v225, v232, s84
	v_mul_lo_u32 v241, v234, s83
	v_mul_lo_u32 v242, v234, s84
	v_readfirstlane_b32 s20, v7
	s_max_i32 s22, s20, 0
	s_sub_i32 s23, s70, s22
	s_add_i32 s23, s23, 2
	v_readfirstlane_b32 s25, v226
	s_mov_b64 s[20:21], -1
	s_cmp_gt_i32 s23, 0
	v_lshlrev_b32_e32 v243, 2, v5
	s_waitcnt vmcnt(3)
	ds_write_b128 v0, v[190:193]
	v_add_u32_e32 v0, v221, v225
	s_waitcnt vmcnt(2)
	ds_write_b128 v0, v[194:197] offset:17408
	v_add_u32_e32 v0, v221, v241
	s_waitcnt vmcnt(1)
	ds_write_b128 v0, v[198:201]
	v_add_u32_e32 v0, v221, v242
	s_waitcnt vmcnt(0)
	ds_write_b128 v0, v[202:205] offset:17408
	s_waitcnt lgkmcnt(0)
	s_barrier
	s_cbranch_scc1 .LBB0_503
	v_lshlrev_b32_e32 v80, 2, v5
	v_xor_b32_e32 v219, 0x80, v80
	s_mov_b64 s[20:21], 0

.LBB0_510:
	s_add_i32 s49, s63, s25
	s_bitcmp1_b32 s25, 0
	s_cselect_b32 s48, 0x9400, 0
	s_add_i32 s48, s48, 0
	v_add3_u32 v0, s48, v249, v248
	v_add_u32_e32 v240, s48, v245
	ds_read_b128 v[142:145], v0
	ds_read_b128 v[146:149], v0 offset:32
	ds_read_b128 v[150:153], v0 offset:64
	ds_read_b128 v[154:157], v0 offset:96
	ds_read_b128 v[2:5], v0 offset:8704
	ds_read_b128 v[6:9], v0 offset:8736
	ds_read_b128 v[10:13], v0 offset:8768
	ds_read_b128 v[208:211], v0 offset:8800
	v_add3_u32 v240, v240, v246, v247
	s_cmp_lg_u32 s49, 0
	s_waitcnt lgkmcnt(7)
	v_mfma_f32_32x32x16_bf16 v[158:173], v[142:145], v[174:177], v[80:95]
	s_waitcnt lgkmcnt(6)
	v_mfma_f32_32x32x16_bf16 v[158:173], v[146:149], v[178:181], v[158:173]
	s_waitcnt lgkmcnt(5)
	v_mfma_f32_32x32x16_bf16 v[158:173], v[150:153], v[182:185], v[158:173]
	s_waitcnt lgkmcnt(4)
	v_mfma_f32_32x32x16_bf16 v[158:173], v[154:157], v[186:189], v[158:173]
	s_waitcnt lgkmcnt(3)
	v_mfma_f32_32x32x16_bf16 v[142:157], v[2:5], v[174:177], v[96:111]
	s_waitcnt lgkmcnt(2)
	v_mfma_f32_32x32x16_bf16 v[142:157], v[6:9], v[178:181], v[142:157]
	s_waitcnt lgkmcnt(1)
	v_mfma_f32_32x32x16_bf16 v[142:157], v[10:13], v[182:185], v[142:157]
	s_waitcnt lgkmcnt(0)
	v_mfma_f32_32x32x16_bf16 v[142:157], v[208:211], v[186:189], v[142:157]
	ds_read_b64_tr_b16 v[2:3], v240 offset:17408
	ds_read_b64_tr_b16 v[4:5], v240 offset:19968
	ds_read_b64_tr_b16 v[6:7], v240 offset:17472
	ds_read_b64_tr_b16 v[8:9], v240 offset:20032
	ds_read_b64_tr_b16 v[10:11], v240 offset:17536
	ds_read_b64_tr_b16 v[12:13], v240 offset:20096
	ds_read_b64_tr_b16 v[208:209], v240 offset:17600
	ds_read_b64_tr_b16 v[210:211], v240 offset:20160
	ds_read_b64_tr_b16 v[212:213], v240 offset:22528
	ds_read_b64_tr_b16 v[214:215], v240 offset:25088
	s_cbranch_scc0 .LBB0_512
	v_cvt_f32_i32_e32 v0, s49
	v_fmamk_f32 v0, v0, 0x42800000, v244
	v_mul_f32_e64 v0, v0, -v226
	s_cmp_eq_u32 s100, 0
	s_cbranch_scc1 .LBB0_515
	s_branch .LBB0_513
.LBB0_512:
	v_sub_f32_e32 v0, v173, v95
	v_sub_f32_e64 v173, v0, |v119|
	v_sub_f32_e32 v0, v172, v94
	v_sub_f32_e64 v172, v0, |v120|
	v_sub_f32_e32 v0, v171, v93
	v_fma_f32 v239, v226, v244, -v93
	v_sub_f32_e64 v171, v0, |v239|
	v_sub_f32_e32 v0, v170, v92
	v_sub_f32_e64 v170, v0, |v112|
	v_sub_f32_e32 v0, v169, v91
	v_sub_f32_e64 v169, v0, |v121|
	v_sub_f32_e32 v0, v168, v90
	v_sub_f32_e64 v168, v0, |v122|
	v_sub_f32_e32 v0, v167, v89
	v_sub_f32_e64 v167, v0, |v113|
	v_sub_f32_e32 v0, v166, v88
	v_sub_f32_e64 v166, v0, |v114|
	v_sub_f32_e32 v0, v165, v87
	v_sub_f32_e64 v165, v0, |v123|
	v_sub_f32_e32 v0, v164, v86
	v_sub_f32_e64 v164, v0, |v124|
	v_sub_f32_e32 v0, v163, v85
	v_sub_f32_e64 v163, v0, |v115|
	v_sub_f32_e32 v0, v162, v84
	v_sub_f32_e64 v162, v0, |v116|
	v_sub_f32_e32 v0, v161, v83
	v_fma_f32 v15, v226, v244, -v83
	v_sub_f32_e64 v161, v0, |v15|
	v_sub_f32_e32 v0, v160, v82
	v_fma_f32 v14, v226, v244, -v82
	v_sub_f32_e64 v160, v0, |v14|
	v_sub_f32_e32 v0, v159, v81
	v_sub_f32_e64 v159, v0, |v117|
	v_sub_f32_e32 v0, v158, v80
	v_sub_f32_e64 v158, v0, |v118|
	v_sub_f32_e32 v0, v157, v111
	v_sub_f32_e64 v157, v0, |v135|
	v_sub_f32_e32 v0, v156, v110
	v_sub_f32_e64 v156, v0, |v136|
	v_sub_f32_e32 v0, v155, v109
	v_sub_f32_e64 v155, v0, |v125|
	v_sub_f32_e32 v0, v154, v108
	v_sub_f32_e64 v154, v0, |v126|
	v_sub_f32_e32 v0, v153, v107
	v_sub_f32_e64 v153, v0, |v137|
	v_sub_f32_e32 v0, v152, v106
	v_sub_f32_e64 v152, v0, |v138|
	v_sub_f32_e32 v0, v151, v105
	v_sub_f32_e64 v151, v0, |v127|
	v_sub_f32_e32 v0, v150, v104
	v_sub_f32_e64 v150, v0, |v128|
	v_sub_f32_e32 v0, v149, v103
	v_sub_f32_e64 v149, v0, |v139|
	v_sub_f32_e32 v0, v148, v102
	v_sub_f32_e64 v148, v0, |v140|
	v_sub_f32_e32 v0, v147, v101
	v_sub_f32_e64 v147, v0, |v129|
	v_sub_f32_e32 v0, v146, v100
	v_sub_f32_e64 v146, v0, |v130|
	v_sub_f32_e32 v0, v145, v99
	v_sub_f32_e64 v145, v0, |v133|
	v_sub_f32_e32 v0, v144, v98
	v_sub_f32_e64 v144, v0, |v134|
	v_sub_f32_e32 v0, v143, v97
	v_sub_f32_e64 v143, v0, |v131|
	v_sub_f32_e32 v0, v142, v96
	v_sub_f32_e64 v142, v0, |v132|
	v_mov_b32_e32 v0, 0
.LBB0_513:
	v_max3_f32 v14, v158, v159, v160
	v_max3_f32 v15, v161, v162, v163
	v_max3_f32 v14, v14, v164, v165
	v_max3_f32 v15, v15, v166, v167
	v_max3_f32 v14, v14, v168, v169
	v_max3_f32 v15, v15, v170, v171
	v_max3_f32 v14, v14, v172, v173
	s_nop 0
	v_max3_f32 v15, v15, v142, v143
	v_max3_f32 v14, v14, v144, v145
	v_max3_f32 v15, v15, v146, v147
	v_max3_f32 v14, v14, v148, v149
	v_max3_f32 v15, v15, v150, v151
	v_max3_f32 v14, v14, v152, v153
	v_max3_f32 v15, v15, v154, v155
	v_max3_f32 v14, v14, v156, v157
	v_max_f32_e32 v14, v14, v15
	v_mov_b32_e32 v15, v14
	s_nop 1
	v_permlane32_swap_b32_e32 v14, v15
	v_max_f32_e32 v14, v14, v15
	v_add_f32_e32 v14, v0, v14
	v_cmp_gt_f32_e32 vcc, v14, v251
	s_cbranch_vccz .LBB0_515
	v_max_f32_e32 v14, v14, v14
	v_max_f32_e32 v15, v251, v251
	v_max_f32_e32 v15, v15, v14
	v_sub_f32_e32 v14, v251, v15
	v_exp_f32_e32 v14, v14
	v_mov_b32_e32 v251, v15
	v_pk_mul_f32 v[78:79], v[78:79], v[14:15] op_sel_hi:[1,0]
	v_pk_mul_f32 v[76:77], v[76:77], v[14:15] op_sel_hi:[1,0]
	v_pk_mul_f32 v[74:75], v[74:75], v[14:15] op_sel_hi:[1,0]
	v_pk_mul_f32 v[72:73], v[72:73], v[14:15] op_sel_hi:[1,0]
	v_pk_mul_f32 v[70:71], v[70:71], v[14:15] op_sel_hi:[1,0]
	v_pk_mul_f32 v[68:69], v[68:69], v[14:15] op_sel_hi:[1,0]
	v_pk_mul_f32 v[66:67], v[66:67], v[14:15] op_sel_hi:[1,0]
	v_pk_mul_f32 v[64:65], v[64:65], v[14:15] op_sel_hi:[1,0]
	v_pk_mul_f32 v[62:63], v[62:63], v[14:15] op_sel_hi:[1,0]
	v_pk_mul_f32 v[60:61], v[60:61], v[14:15] op_sel_hi:[1,0]
	v_pk_mul_f32 v[58:59], v[58:59], v[14:15] op_sel_hi:[1,0]
	v_pk_mul_f32 v[56:57], v[56:57], v[14:15] op_sel_hi:[1,0]
	v_pk_mul_f32 v[54:55], v[54:55], v[14:15] op_sel_hi:[1,0]
	v_pk_mul_f32 v[52:53], v[52:53], v[14:15] op_sel_hi:[1,0]
	v_pk_mul_f32 v[50:51], v[50:51], v[14:15] op_sel_hi:[1,0]
	v_pk_mul_f32 v[48:49], v[48:49], v[14:15] op_sel_hi:[1,0]
	v_pk_mul_f32 v[46:47], v[46:47], v[14:15] op_sel_hi:[1,0]
	v_pk_mul_f32 v[44:45], v[44:45], v[14:15] op_sel_hi:[1,0]
	v_pk_mul_f32 v[42:43], v[42:43], v[14:15] op_sel_hi:[1,0]
	v_pk_mul_f32 v[40:41], v[40:41], v[14:15] op_sel_hi:[1,0]
	v_pk_mul_f32 v[38:39], v[38:39], v[14:15] op_sel_hi:[1,0]
	v_pk_mul_f32 v[36:37], v[36:37], v[14:15] op_sel_hi:[1,0]
	v_pk_mul_f32 v[34:35], v[34:35], v[14:15] op_sel_hi:[1,0]
	v_pk_mul_f32 v[32:33], v[32:33], v[14:15] op_sel_hi:[1,0]
	v_pk_mul_f32 v[30:31], v[30:31], v[14:15] op_sel_hi:[1,0]
	v_pk_mul_f32 v[28:29], v[28:29], v[14:15] op_sel_hi:[1,0]
	v_pk_mul_f32 v[26:27], v[26:27], v[14:15] op_sel_hi:[1,0]
	v_pk_mul_f32 v[24:25], v[24:25], v[14:15] op_sel_hi:[1,0]
	v_pk_mul_f32 v[22:23], v[22:23], v[14:15] op_sel_hi:[1,0]
	v_pk_mul_f32 v[20:21], v[20:21], v[14:15] op_sel_hi:[1,0]
	v_pk_mul_f32 v[18:19], v[18:19], v[14:15] op_sel_hi:[1,0]
	v_pk_mul_f32 v[16:17], v[16:17], v[14:15] op_sel_hi:[1,0]
	v_mul_f32_e32 v250, v250, v14
.LBB0_515:
	v_sub_f32_e32 v0, v251, v0
	v_sub_f32_e32 v158, v158, v0
	v_sub_f32_e32 v159, v159, v0
	v_exp_f32_e32 v158, v158
	v_exp_f32_e32 v159, v159
	v_add_f32_e32 v14, 0, v158
	v_add_f32_e32 v14, v159, v14
	v_cvt_pk_bf16_f32 v158, v158, v159
	v_sub_f32_e32 v160, v160, v0
	v_sub_f32_e32 v161, v161, v0
	v_exp_f32_e32 v160, v160
	v_exp_f32_e32 v161, v161
	v_add_f32_e32 v14, v160, v14
	v_add_f32_e32 v14, v161, v14
	v_cvt_pk_bf16_f32 v159, v160, v161
	v_sub_f32_e32 v162, v162, v0
	v_sub_f32_e32 v163, v163, v0
	v_exp_f32_e32 v162, v162
	v_exp_f32_e32 v163, v163
	v_add_f32_e32 v14, v162, v14
	v_add_f32_e32 v14, v163, v14
	v_cvt_pk_bf16_f32 v160, v162, v163
	v_sub_f32_e32 v164, v164, v0
	v_sub_f32_e32 v165, v165, v0
	v_exp_f32_e32 v164, v164
	v_exp_f32_e32 v165, v165
	v_add_f32_e32 v14, v164, v14
	v_add_f32_e32 v14, v165, v14
	v_cvt_pk_bf16_f32 v161, v164, v165
	ds_read_b64_tr_b16 v[162:163], v240 offset:22592
	ds_read_b64_tr_b16 v[164:165], v240 offset:25152
	s_waitcnt lgkmcnt(10)
	v_mfma_f32_32x32x16_bf16 v[64:79], v[2:5], v[158:161], v[64:79]
	ds_read_b64_tr_b16 v[2:3], v240 offset:22656
	ds_read_b64_tr_b16 v[4:5], v240 offset:25216
	v_sub_f32_e32 v166, v166, v0
	v_sub_f32_e32 v167, v167, v0
	v_exp_f32_e32 v166, v166
	v_exp_f32_e32 v167, v167
	v_add_f32_e32 v14, v166, v14
	v_add_f32_e32 v14, v167, v14
	v_cvt_pk_bf16_f32 v166, v166, v167
	s_waitcnt lgkmcnt(10)
	v_mfma_f32_32x32x16_bf16 v[48:63], v[6:9], v[158:161], v[48:63]
	ds_read_b64_tr_b16 v[6:7], v240 offset:22720
	ds_read_b64_tr_b16 v[8:9], v240 offset:25280
	v_sub_f32_e32 v168, v168, v0
	v_sub_f32_e32 v169, v169, v0
	v_exp_f32_e32 v168, v168
	v_exp_f32_e32 v169, v169
	v_add_f32_e32 v14, v168, v14
	v_add_f32_e32 v14, v169, v14
	v_cvt_pk_bf16_f32 v167, v168, v169
	s_waitcnt lgkmcnt(10)
	v_mfma_f32_32x32x16_bf16 v[32:47], v[10:13], v[158:161], v[32:47]
	ds_read_b64_tr_b16 v[10:11], v240 offset:27648
	ds_read_b64_tr_b16 v[12:13], v240 offset:30208
	v_sub_f32_e32 v170, v170, v0
	v_sub_f32_e32 v171, v171, v0
	v_exp_f32_e32 v170, v170
	v_exp_f32_e32 v171, v171
	v_add_f32_e32 v14, v170, v14
	v_add_f32_e32 v14, v171, v14
	v_cvt_pk_bf16_f32 v168, v170, v171
	s_waitcnt lgkmcnt(10)
	v_mfma_f32_32x32x16_bf16 v[16:31], v[208:211], v[158:161], v[16:31]
	ds_read_b64_tr_b16 v[208:209], v240 offset:27712
	ds_read_b64_tr_b16 v[210:211], v240 offset:30272
	v_sub_f32_e32 v172, v172, v0
	v_sub_f32_e32 v173, v173, v0
	v_exp_f32_e32 v172, v172
	v_exp_f32_e32 v173, v173
	v_add_f32_e32 v14, v172, v14
	v_add_f32_e32 v14, v173, v14
	v_cvt_pk_bf16_f32 v169, v172, v173
	ds_read_b64_tr_b16 v[170:171], v240 offset:27776
	ds_read_b64_tr_b16 v[172:173], v240 offset:30336
	s_waitcnt lgkmcnt(12)
	v_mfma_f32_32x32x16_bf16 v[64:79], v[212:215], v[166:169], v[64:79]
	ds_read_b64_tr_b16 v[212:213], v240 offset:27840
	ds_read_b64_tr_b16 v[214:215], v240 offset:30400
	v_sub_f32_e32 v142, v142, v0
	v_sub_f32_e32 v143, v143, v0
	v_exp_f32_e32 v142, v142
	v_exp_f32_e32 v143, v143
	v_add_f32_e32 v14, v142, v14
	v_add_f32_e32 v14, v143, v14
	v_cvt_pk_bf16_f32 v142, v142, v143
	s_waitcnt lgkmcnt(12)
	v_mfma_f32_32x32x16_bf16 v[48:63], v[162:165], v[166:169], v[48:63]
	ds_read_b64_tr_b16 v[162:163], v240 offset:32768
	ds_read_b64_tr_b16 v[164:165], v240 offset:35328
	v_sub_f32_e32 v144, v144, v0
	v_sub_f32_e32 v145, v145, v0
	v_exp_f32_e32 v144, v144
	v_exp_f32_e32 v145, v145
	v_add_f32_e32 v14, v144, v14
	v_add_f32_e32 v14, v145, v14
	v_cvt_pk_bf16_f32 v143, v144, v145
	s_waitcnt lgkmcnt(12)
	v_mfma_f32_32x32x16_bf16 v[32:47], v[2:5], v[166:169], v[32:47]
	ds_read_b64_tr_b16 v[2:3], v240 offset:32832
	ds_read_b64_tr_b16 v[4:5], v240 offset:35392
	v_sub_f32_e32 v146, v146, v0
	v_sub_f32_e32 v147, v147, v0
	v_exp_f32_e32 v146, v146
	v_exp_f32_e32 v147, v147
	v_add_f32_e32 v14, v146, v14
	v_add_f32_e32 v14, v147, v14
	v_cvt_pk_bf16_f32 v144, v146, v147
	s_waitcnt lgkmcnt(12)
	v_mfma_f32_32x32x16_bf16 v[16:31], v[6:9], v[166:169], v[16:31]
	ds_read_b64_tr_b16 v[6:7], v240 offset:32896
	ds_read_b64_tr_b16 v[8:9], v240 offset:35456
	v_sub_f32_e32 v148, v148, v0
	v_sub_f32_e32 v149, v149, v0
	v_exp_f32_e32 v148, v148
	v_exp_f32_e32 v149, v149
	v_add_f32_e32 v14, v148, v14
	v_add_f32_e32 v14, v149, v14
	v_cvt_pk_bf16_f32 v145, v148, v149
	ds_read_b64_tr_b16 v[146:147], v240 offset:32960
	ds_read_b64_tr_b16 v[148:149], v240 offset:35520
	s_waitcnt lgkmcnt(14)
	v_mfma_f32_32x32x16_bf16 v[64:79], v[10:13], v[142:145], v[64:79]
	v_sub_f32_e32 v150, v150, v0
	v_sub_f32_e32 v151, v151, v0
	v_exp_f32_e32 v150, v150
	v_exp_f32_e32 v151, v151
	v_add_f32_e32 v14, v150, v14
	v_add_f32_e32 v14, v151, v14
	v_cvt_pk_bf16_f32 v150, v150, v151
	s_waitcnt lgkmcnt(12)
	v_mfma_f32_32x32x16_bf16 v[48:63], v[208:211], v[142:145], v[48:63]
	v_sub_f32_e32 v152, v152, v0
	v_sub_f32_e32 v153, v153, v0
	v_exp_f32_e32 v152, v152
	v_exp_f32_e32 v153, v153
	v_add_f32_e32 v14, v152, v14
	v_add_f32_e32 v14, v153, v14
	v_cvt_pk_bf16_f32 v151, v152, v153
	s_waitcnt lgkmcnt(10)
	v_mfma_f32_32x32x16_bf16 v[32:47], v[170:173], v[142:145], v[32:47]
	v_sub_f32_e32 v154, v154, v0
	v_sub_f32_e32 v155, v155, v0
	v_exp_f32_e32 v154, v154
	v_exp_f32_e32 v155, v155
	v_add_f32_e32 v14, v154, v14
	v_add_f32_e32 v14, v155, v14
	v_cvt_pk_bf16_f32 v152, v154, v155
	s_waitcnt lgkmcnt(8)
	v_mfma_f32_32x32x16_bf16 v[16:31], v[212:215], v[142:145], v[16:31]
	v_sub_f32_e32 v156, v156, v0
	v_sub_f32_e32 v157, v157, v0
	v_exp_f32_e32 v156, v156
	v_exp_f32_e32 v157, v157
	v_add_f32_e32 v14, v156, v14
	v_add_f32_e32 v14, v157, v14
	v_cvt_pk_bf16_f32 v153, v156, v157
	s_nop 0
	s_waitcnt lgkmcnt(6)
	v_mfma_f32_32x32x16_bf16 v[64:79], v[162:165], v[150:153], v[64:79]
	s_waitcnt lgkmcnt(4)
	v_mfma_f32_32x32x16_bf16 v[48:63], v[2:5], v[150:153], v[48:63]
	s_waitcnt lgkmcnt(2)
	v_mfma_f32_32x32x16_bf16 v[32:47], v[6:9], v[150:153], v[32:47]
	s_waitcnt lgkmcnt(0)
	v_mfma_f32_32x32x16_bf16 v[16:31], v[146:149], v[150:153], v[16:31]
	v_add_f32_e32 v250, v250, v14
	s_andn2_b64 vcc, exec, s[20:21]
	s_cbranch_vccnz .LBB0_505

.LBB0_519:
	ds_bpermute_b32 v0, v219, v250
	s_waitcnt lgkmcnt(0)
	v_add_f32_e32 v0, v250, v0
	s_cmp_lg_u32 s100, 0
	s_cbranch_scc1 .Lattn_guard_done
	v_cmp_ngt_f32_e32 vcc, 0x71800000, v0
	s_cbranch_vccz .Lattn_guard_done
	v_mov_b32_e32 v142, s85
	v_mov_b32_e32 v143, 1
	ds_write_b32 v142, v143 offset:32
.Lattn_guard_done:
	v_div_scale_f32 v2, s[20:21], v0, v0, 1.0
	v_rcp_f32_e32 v3, v2
	v_div_scale_f32 v4, vcc, 1.0, v0, 1.0
	v_fma_f32 v5, -v2, v3, 1.0
	v_fmac_f32_e32 v3, v5, v3
	v_mul_f32_e32 v5, v4, v3
	v_fma_f32 v6, -v2, v5, v4
	v_fmac_f32_e32 v5, v6, v3
	v_fma_f32 v2, -v2, v5, v4
	v_div_fmas_f32 v2, v2, v3, v5
	s_and_b64 vcc, exec, s[38:39]
	v_div_fixup_f32 v2, v2, v0, 1.0
	s_cbranch_vccnz .LBB0_521
	v_mul_f32_e32 v0, v64, v2
	v_add_u32_e32 v3, s78, v80
	v_mul_f32_e32 v4, v65, v2
	ds_write2st64_b32 v3, v0, v4 offset1:1
	v_mul_f32_e32 v0, v66, v2
	v_mul_f32_e32 v4, v67, v2
	ds_write2st64_b32 v3, v0, v4 offset0:2 offset1:3
	v_mul_f32_e32 v0, v68, v2
	v_mul_f32_e32 v4, v69, v2
	ds_write2st64_b32 v3, v0, v4 offset0:4 offset1:5
	v_mul_f32_e32 v0, v70, v2
	v_mul_f32_e32 v4, v71, v2
	ds_write2st64_b32 v3, v0, v4 offset0:6 offset1:7
	v_mul_f32_e32 v0, v72, v2
	v_mul_f32_e32 v4, v73, v2
	ds_write2st64_b32 v3, v0, v4 offset0:8 offset1:9
	v_mul_f32_e32 v0, v74, v2
	v_mul_f32_e32 v4, v75, v2
	ds_write2st64_b32 v3, v0, v4 offset0:10 offset1:11
	v_mul_f32_e32 v0, v76, v2
	v_mul_f32_e32 v4, v77, v2
	ds_write2st64_b32 v3, v0, v4 offset0:12 offset1:13
	v_mul_f32_e32 v0, v78, v2
	v_mul_f32_e32 v4, v79, v2
	ds_write2st64_b32 v3, v0, v4 offset0:14 offset1:15
	v_mul_f32_e32 v0, v48, v2
	v_mul_f32_e32 v4, v49, v2
	ds_write2st64_b32 v3, v0, v4 offset0:16 offset1:17
	v_mul_f32_e32 v0, v50, v2
	v_mul_f32_e32 v4, v51, v2
	ds_write2st64_b32 v3, v0, v4 offset0:18 offset1:19
	v_mul_f32_e32 v0, v52, v2
	v_mul_f32_e32 v4, v53, v2
	ds_write2st64_b32 v3, v0, v4 offset0:20 offset1:21
	v_mul_f32_e32 v0, v54, v2
	v_mul_f32_e32 v4, v55, v2
	ds_write2st64_b32 v3, v0, v4 offset0:22 offset1:23
	v_mul_f32_e32 v0, v56, v2
	v_mul_f32_e32 v4, v57, v2
	ds_write2st64_b32 v3, v0, v4 offset0:24 offset1:25
	v_mul_f32_e32 v0, v58, v2
	v_mul_f32_e32 v4, v59, v2
	ds_write2st64_b32 v3, v0, v4 offset0:26 offset1:27
	v_mul_f32_e32 v0, v60, v2
	v_mul_f32_e32 v4, v61, v2
	ds_write2st64_b32 v3, v0, v4 offset0:28 offset1:29
	v_mul_f32_e32 v0, v62, v2
	v_mul_f32_e32 v4, v63, v2
	ds_write2st64_b32 v3, v0, v4 offset0:30 offset1:31
	v_mul_f32_e32 v0, v32, v2
	v_mul_f32_e32 v4, v33, v2
	ds_write2st64_b32 v3, v0, v4 offset0:32 offset1:33
	v_mul_f32_e32 v0, v34, v2
	v_mul_f32_e32 v4, v35, v2
	ds_write2st64_b32 v3, v0, v4 offset0:34 offset1:35
	v_mul_f32_e32 v0, v36, v2
	v_mul_f32_e32 v4, v37, v2
	ds_write2st64_b32 v3, v0, v4 offset0:36 offset1:37
	v_mul_f32_e32 v0, v38, v2
	v_mul_f32_e32 v4, v39, v2
	ds_write2st64_b32 v3, v0, v4 offset0:38 offset1:39
	v_mul_f32_e32 v0, v40, v2
	v_mul_f32_e32 v4, v41, v2
	ds_write2st64_b32 v3, v0, v4 offset0:40 offset1:41
	v_mul_f32_e32 v0, v42, v2
	v_mul_f32_e32 v4, v43, v2
	ds_write2st64_b32 v3, v0, v4 offset0:42 offset1:43
	v_mul_f32_e32 v0, v44, v2
	v_mul_f32_e32 v4, v45, v2
	ds_write2st64_b32 v3, v0, v4 offset0:44 offset1:45
	v_mul_f32_e32 v0, v46, v2
	v_mul_f32_e32 v4, v47, v2
	ds_write2st64_b32 v3, v0, v4 offset0:46 offset1:47
	v_mul_f32_e32 v0, v16, v2
	v_mul_f32_e32 v4, v17, v2
	ds_write2st64_b32 v3, v0, v4 offset0:48 offset1:49
	v_mul_f32_e32 v0, v18, v2
	v_mul_f32_e32 v4, v19, v2
	ds_write2st64_b32 v3, v0, v4 offset0:50 offset1:51
	v_mul_f32_e32 v0, v20, v2
	v_mul_f32_e32 v4, v21, v2
	ds_write2st64_b32 v3, v0, v4 offset0:52 offset1:53
	v_mul_f32_e32 v0, v22, v2
	v_mul_f32_e32 v4, v23, v2
	ds_write2st64_b32 v3, v0, v4 offset0:54 offset1:55
	v_mul_f32_e32 v0, v24, v2
	v_mul_f32_e32 v4, v25, v2
	ds_write2st64_b32 v3, v0, v4 offset0:56 offset1:57
	v_mul_f32_e32 v0, v26, v2
	v_mul_f32_e32 v4, v27, v2
	ds_write2st64_b32 v3, v0, v4 offset0:58 offset1:59
	v_mul_f32_e32 v0, v28, v2
	v_mul_f32_e32 v4, v29, v2
	ds_write2st64_b32 v3, v0, v4 offset0:60 offset1:61
	v_mul_f32_e32 v0, v30, v2
	v_mul_f32_e32 v4, v31, v2
	ds_write2st64_b32 v3, v0, v4 offset0:62 offset1:63
.LBB0_521:
	s_andn2_b64 vcc, exec, s[16:17]
	s_waitcnt lgkmcnt(0)
	s_barrier
	v_mov_b32_e32 v142, s85
	ds_read_b32 v143, v142 offset:32
	s_waitcnt lgkmcnt(0)
	v_readfirstlane_b32 s101, v143
	s_cmp_lg_u32 s101, 0
	s_cbranch_scc0 .Lattn_no_rerun
	s_barrier
	v_mov_b32_e32 v143, 0
	ds_write_b32 v142, v143 offset:32
	ds_read_b32 v0, v142
	s_mov_b32 s100, 1
	s_waitcnt lgkmcnt(0)
	v_readfirstlane_b32 s22, v0
	s_barrier
	s_branch .Lattn_item_start
.Lattn_no_rerun:
	s_cbranch_vccnz .LBB0_494
	v_add_u32_e32 v8, s33, v80
	ds_read2st64_b32 v[84:85], v8 offset1:1
	ds_read2st64_b32 v[86:87], v8 offset0:2 offset1:3
	ds_read2st64_b32 v[88:89], v8 offset0:4 offset1:5
	ds_read2st64_b32 v[90:91], v8 offset0:6 offset1:7
	ds_read2st64_b32 v[92:93], v8 offset0:8 offset1:9
	ds_read2st64_b32 v[94:95], v8 offset0:10 offset1:11
	ds_read2st64_b32 v[96:97], v8 offset0:12 offset1:13
	ds_read2st64_b32 v[98:99], v8 offset0:14 offset1:15
	ds_read2st64_b32 v[100:101], v8 offset0:16 offset1:17
	ds_read2st64_b32 v[102:103], v8 offset0:18 offset1:19
	ds_read2st64_b32 v[104:105], v8 offset0:20 offset1:21
	ds_read2st64_b32 v[106:107], v8 offset0:22 offset1:23
	ds_read2st64_b32 v[108:109], v8 offset0:24 offset1:25
	ds_read2st64_b32 v[110:111], v8 offset0:26 offset1:27
	ds_read2st64_b32 v[112:113], v8 offset0:28 offset1:29
	ds_read2st64_b32 v[114:115], v8 offset0:30 offset1:31
	ds_read2st64_b32 v[116:117], v8 offset0:32 offset1:33
	ds_read2st64_b32 v[118:119], v8 offset0:34 offset1:35
	ds_read2st64_b32 v[120:121], v8 offset0:36 offset1:37
	ds_read2st64_b32 v[122:123], v8 offset0:38 offset1:39
	ds_read2st64_b32 v[124:125], v8 offset0:40 offset1:41
	ds_read2st64_b32 v[126:127], v8 offset0:42 offset1:43
	ds_read2st64_b32 v[128:129], v8 offset0:44 offset1:45
	ds_read2st64_b32 v[130:131], v8 offset0:46 offset1:47
	ds_read2st64_b32 v[132:133], v8 offset0:48 offset1:49
	ds_read2st64_b32 v[134:135], v8 offset0:50 offset1:51
	ds_read2st64_b32 v[136:137], v8 offset0:52 offset1:53
	ds_read2st64_b32 v[138:139], v8 offset0:54 offset1:55
	ds_read2st64_b32 v[210:211], v8 offset0:56 offset1:57
	ds_read2st64_b32 v[212:213], v8 offset0:58 offset1:59
	ds_read2st64_b32 v[214:215], v8 offset0:60 offset1:61
	ds_read2st64_b32 v[82:83], v8 offset0:62 offset1:63
	v_mov_b32_e32 v5, s14
	v_mov_b32_e32 v4, v64
	v_ashrrev_i32_e32 v225, 31, v224
	v_lshl_add_u64 v[208:209], v[224:225], 2, s[0:1]
	global_load_dwordx4 v[142:145], v[208:209], off
	global_load_dwordx4 v[146:149], v[208:209], off offset:32
	global_load_dwordx4 v[150:153], v[208:209], off offset:64
	global_load_dwordx4 v[154:157], v[208:209], off offset:96
	global_load_dwordx4 v[158:161], v[208:209], off offset:128
	global_load_dwordx4 v[162:165], v[208:209], off offset:160
	global_load_dwordx4 v[166:169], v[208:209], off offset:192
	global_load_dwordx4 v[170:173], v[208:209], off offset:224
	global_load_dwordx4 v[174:177], v[208:209], off offset:256
	global_load_dwordx4 v[178:181], v[208:209], off offset:288
	global_load_dwordx4 v[182:185], v[208:209], off offset:320
	global_load_dwordx4 v[186:189], v[208:209], off offset:352
	global_load_dwordx4 v[190:193], v[208:209], off offset:384
	global_load_dwordx4 v[194:197], v[208:209], off offset:416
	global_load_dwordx4 v[198:201], v[208:209], off offset:448
	global_load_dwordx4 v[202:205], v[208:209], off offset:480
	v_ashrrev_i32_e32 v223, 31, v222
	s_waitcnt lgkmcnt(15)
	v_mov_b32_e32 v3, v84
	v_pk_mul_f32 v[10:11], v[4:5], v[2:3]
	v_mov_b32_e32 v4, v65
	v_mov_b32_e32 v3, v85
	v_pk_mul_f32 v[6:7], v[4:5], v[2:3]
	v_mov_b32_e32 v4, v66
	v_sub_f32_e32 v12, v6, v7
	v_sub_f32_e32 v0, v10, v11
	v_ashrrev_i32_e32 v221, 31, v220
	s_waitcnt lgkmcnt(15)
	v_mov_b32_e32 v3, v86
	v_pk_mul_f32 v[10:11], v[4:5], v[2:3]
	v_mov_b32_e32 v4, v67
	v_mov_b32_e32 v3, v87
	v_pk_mul_f32 v[6:7], v[4:5], v[2:3]
	v_mov_b32_e32 v4, v68
	v_sub_f32_e32 v14, v6, v7
	v_sub_f32_e32 v13, v10, v11
	s_waitcnt lgkmcnt(15)
	v_mov_b32_e32 v3, v88
	v_pk_mul_f32 v[10:11], v[4:5], v[2:3]
	v_mov_b32_e32 v4, v69
	v_mov_b32_e32 v3, v89
	v_pk_mul_f32 v[6:7], v[4:5], v[2:3]
	v_mov_b32_e32 v4, v70
	v_sub_f32_e32 v64, v6, v7
	v_sub_f32_e32 v15, v10, v11
	s_waitcnt lgkmcnt(15)
	v_mov_b32_e32 v3, v90
	v_pk_mul_f32 v[10:11], v[4:5], v[2:3]
	v_mov_b32_e32 v4, v71
	v_mov_b32_e32 v3, v91
	v_pk_mul_f32 v[6:7], v[4:5], v[2:3]
	v_mov_b32_e32 v4, v72
	v_sub_f32_e32 v66, v6, v7
	v_sub_f32_e32 v65, v10, v11
	s_waitcnt lgkmcnt(15)
	v_mov_b32_e32 v3, v92
	v_pk_mul_f32 v[10:11], v[4:5], v[2:3]
	v_mov_b32_e32 v4, v73
	v_mov_b32_e32 v3, v93
	v_pk_mul_f32 v[6:7], v[4:5], v[2:3]
	v_mov_b32_e32 v4, v74
	v_sub_f32_e32 v68, v6, v7
	v_sub_f32_e32 v67, v10, v11
	s_waitcnt lgkmcnt(15)
	v_mov_b32_e32 v3, v94
	v_pk_mul_f32 v[10:11], v[4:5], v[2:3]
	v_mov_b32_e32 v4, v75
	v_mov_b32_e32 v3, v95
	v_pk_mul_f32 v[6:7], v[4:5], v[2:3]
	v_mov_b32_e32 v4, v76
	v_sub_f32_e32 v70, v6, v7
	v_sub_f32_e32 v69, v10, v11
	s_waitcnt lgkmcnt(15)
	v_mov_b32_e32 v3, v96
	v_pk_mul_f32 v[10:11], v[4:5], v[2:3]
	v_mov_b32_e32 v4, v77
	v_mov_b32_e32 v3, v97
	v_pk_mul_f32 v[6:7], v[4:5], v[2:3]
	v_mov_b32_e32 v4, v78
	v_sub_f32_e32 v72, v6, v7
	v_sub_f32_e32 v71, v10, v11
	s_waitcnt lgkmcnt(15)
	v_mov_b32_e32 v3, v98
	v_pk_mul_f32 v[10:11], v[4:5], v[2:3]
	v_mov_b32_e32 v4, v79
	v_mov_b32_e32 v3, v99
	v_pk_mul_f32 v[6:7], v[4:5], v[2:3]
	v_mov_b32_e32 v4, v48
	v_sub_f32_e32 v74, v6, v7
	v_sub_f32_e32 v73, v10, v11
	s_waitcnt lgkmcnt(15)
	v_mov_b32_e32 v3, v100
	v_pk_mul_f32 v[10:11], v[4:5], v[2:3]
	v_mov_b32_e32 v4, v49
	v_mov_b32_e32 v3, v101
	v_pk_mul_f32 v[6:7], v[4:5], v[2:3]
	v_mov_b32_e32 v4, v50
	v_sub_f32_e32 v49, v6, v7
	v_sub_f32_e32 v48, v10, v11
	s_waitcnt lgkmcnt(15)
	v_mov_b32_e32 v3, v102
	v_pk_mul_f32 v[10:11], v[4:5], v[2:3]
	v_mov_b32_e32 v4, v51
	v_mov_b32_e32 v3, v103
	v_pk_mul_f32 v[6:7], v[4:5], v[2:3]
	v_mov_b32_e32 v4, v52
	v_sub_f32_e32 v51, v6, v7
	v_sub_f32_e32 v50, v10, v11
	s_waitcnt lgkmcnt(15)
	v_mov_b32_e32 v3, v104
	v_pk_mul_f32 v[10:11], v[4:5], v[2:3]
	v_mov_b32_e32 v4, v53
	v_mov_b32_e32 v3, v105
	v_pk_mul_f32 v[6:7], v[4:5], v[2:3]
	v_mov_b32_e32 v4, v54
	v_sub_f32_e32 v52, v6, v7
	v_sub_f32_e32 v75, v10, v11
	s_waitcnt lgkmcnt(15)
	v_mov_b32_e32 v3, v106
	v_pk_mul_f32 v[10:11], v[4:5], v[2:3]
	v_mov_b32_e32 v4, v55
	v_mov_b32_e32 v3, v107
	v_pk_mul_f32 v[6:7], v[4:5], v[2:3]
	v_mov_b32_e32 v4, v56
	v_sub_f32_e32 v55, v6, v7
	v_sub_f32_e32 v76, v10, v11
	s_waitcnt lgkmcnt(15)
	v_mov_b32_e32 v3, v108
	v_pk_mul_f32 v[10:11], v[4:5], v[2:3]
	v_mov_b32_e32 v4, v57
	v_mov_b32_e32 v3, v109
	v_pk_mul_f32 v[6:7], v[4:5], v[2:3]
	v_mov_b32_e32 v4, v58
	v_sub_f32_e32 v53, v6, v7
	v_sub_f32_e32 v54, v10, v11
	s_waitcnt lgkmcnt(15)
	v_mov_b32_e32 v3, v110
	v_pk_mul_f32 v[10:11], v[4:5], v[2:3]
	v_mov_b32_e32 v4, v59
	v_mov_b32_e32 v3, v111
	v_pk_mul_f32 v[6:7], v[4:5], v[2:3]
	v_mov_b32_e32 v4, v60
	v_sub_f32_e32 v56, v6, v7
	v_sub_f32_e32 v57, v10, v11
	s_waitcnt lgkmcnt(15)
	v_mov_b32_e32 v3, v112
	v_pk_mul_f32 v[10:11], v[4:5], v[2:3]
	v_mov_b32_e32 v4, v61
	v_mov_b32_e32 v3, v113
	v_pk_mul_f32 v[6:7], v[4:5], v[2:3]
	v_mov_b32_e32 v4, v62
	v_sub_f32_e32 v58, v6, v7
	v_sub_f32_e32 v59, v10, v11
	s_waitcnt lgkmcnt(15)
	v_mov_b32_e32 v3, v114
	v_pk_mul_f32 v[10:11], v[4:5], v[2:3]
	v_mov_b32_e32 v4, v63
	v_mov_b32_e32 v3, v115
	v_pk_mul_f32 v[6:7], v[4:5], v[2:3]
	v_mov_b32_e32 v4, v32
	v_sub_f32_e32 v60, v6, v7
	v_sub_f32_e32 v62, v10, v11
	s_waitcnt lgkmcnt(15)
	v_mov_b32_e32 v3, v116
	v_pk_mul_f32 v[10:11], v[4:5], v[2:3]
	v_mov_b32_e32 v4, v33
	v_mov_b32_e32 v3, v117
	v_pk_mul_f32 v[6:7], v[4:5], v[2:3]
	v_mov_b32_e32 v4, v34
	v_sub_f32_e32 v32, v6, v7
	v_sub_f32_e32 v61, v10, v11
	s_waitcnt lgkmcnt(14)
	v_mov_b32_e32 v3, v118
	v_pk_mul_f32 v[10:11], v[4:5], v[2:3]
	v_mov_b32_e32 v4, v35
	v_mov_b32_e32 v3, v119
	v_pk_mul_f32 v[6:7], v[4:5], v[2:3]
	v_mov_b32_e32 v4, v36
	v_sub_f32_e32 v33, v6, v7
	v_sub_f32_e32 v34, v10, v11
	s_waitcnt lgkmcnt(13)
	v_mov_b32_e32 v3, v120
	v_pk_mul_f32 v[10:11], v[4:5], v[2:3]
	v_mov_b32_e32 v4, v37
	v_mov_b32_e32 v3, v121
	v_pk_mul_f32 v[6:7], v[4:5], v[2:3]
	v_mov_b32_e32 v4, v38
	v_sub_f32_e32 v35, v6, v7
	v_sub_f32_e32 v36, v10, v11
	s_waitcnt lgkmcnt(12)
	v_mov_b32_e32 v3, v122
	v_pk_mul_f32 v[10:11], v[4:5], v[2:3]
	v_mov_b32_e32 v4, v39
	v_mov_b32_e32 v3, v123
	v_pk_mul_f32 v[6:7], v[4:5], v[2:3]
	v_mov_b32_e32 v4, v40
	v_sub_f32_e32 v39, v6, v7
	v_sub_f32_e32 v63, v10, v11
	s_waitcnt lgkmcnt(11)
	v_mov_b32_e32 v3, v124
	v_pk_mul_f32 v[10:11], v[4:5], v[2:3]
	v_mov_b32_e32 v4, v41
	v_mov_b32_e32 v3, v125
	v_pk_mul_f32 v[6:7], v[4:5], v[2:3]
	v_mov_b32_e32 v4, v42
	v_sub_f32_e32 v37, v6, v7
	v_sub_f32_e32 v38, v10, v11
	s_waitcnt lgkmcnt(10)
	v_mov_b32_e32 v3, v126
	v_pk_mul_f32 v[10:11], v[4:5], v[2:3]
	v_mov_b32_e32 v4, v43
	v_mov_b32_e32 v3, v127
	v_pk_mul_f32 v[6:7], v[4:5], v[2:3]
	v_mov_b32_e32 v4, v44
	v_sub_f32_e32 v40, v6, v7
	v_sub_f32_e32 v41, v10, v11
	s_waitcnt lgkmcnt(9)
	v_mov_b32_e32 v3, v128
	v_pk_mul_f32 v[10:11], v[4:5], v[2:3]
	v_mov_b32_e32 v4, v45
	v_mov_b32_e32 v3, v129
	v_pk_mul_f32 v[6:7], v[4:5], v[2:3]
	v_mov_b32_e32 v4, v46
	v_sub_f32_e32 v42, v6, v7
	v_sub_f32_e32 v43, v10, v11
	s_waitcnt lgkmcnt(8)
	v_mov_b32_e32 v3, v130
	v_pk_mul_f32 v[10:11], v[4:5], v[2:3]
	v_mov_b32_e32 v4, v47
	v_mov_b32_e32 v3, v131
	v_pk_mul_f32 v[6:7], v[4:5], v[2:3]
	v_mov_b32_e32 v4, v16
	v_sub_f32_e32 v45, v6, v7
	v_sub_f32_e32 v46, v10, v11
	s_waitcnt lgkmcnt(7)
	v_mov_b32_e32 v3, v132
	v_pk_mul_f32 v[10:11], v[4:5], v[2:3]
	v_mov_b32_e32 v4, v17
	v_mov_b32_e32 v3, v133
	v_pk_mul_f32 v[6:7], v[4:5], v[2:3]
	v_mov_b32_e32 v4, v18
	v_sub_f32_e32 v16, v6, v7
	v_sub_f32_e32 v44, v10, v11
	s_waitcnt lgkmcnt(6)
	v_mov_b32_e32 v3, v134
	v_pk_mul_f32 v[10:11], v[4:5], v[2:3]
	v_mov_b32_e32 v4, v19
	v_mov_b32_e32 v3, v135
	v_pk_mul_f32 v[6:7], v[4:5], v[2:3]
	v_mov_b32_e32 v4, v20
	v_sub_f32_e32 v17, v6, v7
	v_sub_f32_e32 v18, v10, v11
	s_waitcnt lgkmcnt(5)
	v_mov_b32_e32 v3, v136
	v_pk_mul_f32 v[10:11], v[4:5], v[2:3]
	v_mov_b32_e32 v4, v21
	v_mov_b32_e32 v3, v137
	v_pk_mul_f32 v[6:7], v[4:5], v[2:3]
	v_mov_b32_e32 v4, v22
	v_sub_f32_e32 v19, v6, v7
	v_sub_f32_e32 v20, v10, v11
	s_waitcnt lgkmcnt(4)
	v_mov_b32_e32 v3, v138
	v_pk_mul_f32 v[10:11], v[4:5], v[2:3]
	v_mov_b32_e32 v4, v23
	v_mov_b32_e32 v3, v139
	v_pk_mul_f32 v[6:7], v[4:5], v[2:3]
	v_mov_b32_e32 v4, v24
	v_sub_f32_e32 v23, v6, v7
	v_sub_f32_e32 v47, v10, v11
	s_waitcnt lgkmcnt(3)
	v_mov_b32_e32 v3, v210
	v_pk_mul_f32 v[10:11], v[4:5], v[2:3]
	v_mov_b32_e32 v4, v25
	v_mov_b32_e32 v3, v211
	v_pk_mul_f32 v[6:7], v[4:5], v[2:3]
	v_mov_b32_e32 v4, v26
	v_sub_f32_e32 v21, v6, v7
	v_sub_f32_e32 v22, v10, v11
	s_waitcnt lgkmcnt(2)
	v_mov_b32_e32 v3, v212
	v_pk_mul_f32 v[10:11], v[4:5], v[2:3]
	v_mov_b32_e32 v4, v27
	v_sub_f32_e32 v25, v10, v11
	v_mul_f32_e32 v10, v0, v0
	v_fmac_f32_e32 v10, v12, v12
	v_fmac_f32_e32 v10, v13, v13
	v_fmac_f32_e32 v10, v14, v14
	v_fmac_f32_e32 v10, v15, v15
	v_fmac_f32_e32 v10, v64, v64
	v_fmac_f32_e32 v10, v65, v65
	v_fmac_f32_e32 v10, v66, v66
	v_fmac_f32_e32 v10, v67, v67
	v_fmac_f32_e32 v10, v68, v68
	v_fmac_f32_e32 v10, v69, v69
	v_fmac_f32_e32 v10, v70, v70
	v_fmac_f32_e32 v10, v71, v71
	v_fmac_f32_e32 v10, v72, v72
	v_fmac_f32_e32 v10, v73, v73
	v_fmac_f32_e32 v10, v74, v74
	v_fmac_f32_e32 v10, v48, v48
	v_fmac_f32_e32 v10, v49, v49
	v_fmac_f32_e32 v10, v50, v50
	v_fmac_f32_e32 v10, v51, v51
	v_fmac_f32_e32 v10, v75, v75
	v_fmac_f32_e32 v10, v52, v52
	v_fmac_f32_e32 v10, v76, v76
	v_fmac_f32_e32 v10, v55, v55
	v_fmac_f32_e32 v10, v54, v54
	v_fmac_f32_e32 v10, v53, v53
	v_fmac_f32_e32 v10, v57, v57
	v_fmac_f32_e32 v10, v56, v56
	v_fmac_f32_e32 v10, v59, v59
	v_fmac_f32_e32 v10, v58, v58
	v_fmac_f32_e32 v10, v62, v62
	v_fmac_f32_e32 v10, v60, v60
	v_fmac_f32_e32 v10, v61, v61
	v_fmac_f32_e32 v10, v32, v32
	v_fmac_f32_e32 v10, v34, v34
	v_fmac_f32_e32 v10, v33, v33
	v_fmac_f32_e32 v10, v36, v36
	v_fmac_f32_e32 v10, v35, v35
	v_fmac_f32_e32 v10, v63, v63
	v_fmac_f32_e32 v10, v39, v39
	v_fmac_f32_e32 v10, v38, v38
	v_fmac_f32_e32 v10, v37, v37
	v_fmac_f32_e32 v10, v41, v41
	v_fmac_f32_e32 v10, v40, v40
	v_fmac_f32_e32 v10, v43, v43
	v_fmac_f32_e32 v10, v42, v42
	v_fmac_f32_e32 v10, v46, v46
	v_fmac_f32_e32 v10, v45, v45
	v_fmac_f32_e32 v10, v44, v44
	v_fmac_f32_e32 v10, v16, v16
	v_mov_b32_e32 v3, v213
	v_fmac_f32_e32 v10, v18, v18
	v_pk_mul_f32 v[4:5], v[4:5], v[2:3]
	v_fmac_f32_e32 v10, v17, v17
	v_sub_f32_e32 v24, v4, v5
	v_fmac_f32_e32 v10, v20, v20
	v_fmac_f32_e32 v10, v19, v19
	v_fmac_f32_e32 v10, v47, v47
	v_fmac_f32_e32 v10, v23, v23
	v_fmac_f32_e32 v10, v22, v22
	s_waitcnt lgkmcnt(1)
	v_pk_mul_f32 v[4:5], s[14:15], v[214:215]
	v_fmac_f32_e32 v10, v21, v21
	v_pk_fma_f32 v[6:7], v[28:29], v[2:3], v[4:5] op_sel_hi:[1,0,1] neg_lo:[0,0,1] neg_hi:[0,0,1]
	v_fmac_f32_e32 v10, v25, v25
	v_pk_mul_f32 v[4:5], v[6:7], v[6:7]
	s_waitcnt lgkmcnt(0)
	v_pk_mul_f32 v[8:9], s[14:15], v[82:83]
	v_fmac_f32_e32 v10, v24, v24
	v_pk_fma_f32 v[8:9], v[30:31], v[2:3], v[8:9] op_sel_hi:[1,0,1] neg_lo:[0,0,1] neg_hi:[0,0,1]
	v_add_f32_e32 v4, v10, v4
	v_pk_mul_f32 v[2:3], v[8:9], v[8:9]
	v_add_f32_e32 v4, v4, v5
	v_add_f32_e32 v2, v4, v2
	v_add_f32_e32 v2, v2, v3
	ds_bpermute_b32 v3, v219, v2
	v_ashrrev_i32_e32 v219, 31, v218
	s_waitcnt lgkmcnt(0)
	v_add_f32_e32 v2, v2, v3
	v_fmamk_f32 v2, v2, 0x3c000000, v207
	v_cmp_gt_f32_e32 vcc, s82, v2
	v_mul_f32_e32 v3, 0x4f800000, v2
	s_nop 0
	v_cndmask_b32_e32 v2, v2, v3, vcc
	v_sqrt_f32_e32 v3, v2
	s_nop 0
	v_add_u32_e32 v4, -1, v3
	v_fma_f32 v5, -v4, v3, v2
	v_cmp_ge_f32_e64 s[48:49], 0, v5
	v_add_u32_e32 v5, 1, v3
	s_nop 0
	v_cndmask_b32_e64 v4, v3, v4, s[48:49]
	v_fma_f32 v3, -v5, v3, v2
	v_cmp_lt_f32_e64 s[48:49], 0, v3
	s_nop 1
	v_cndmask_b32_e64 v3, v4, v5, s[48:49]
	v_mul_f32_e32 v4, 0x37800000, v3
	v_cndmask_b32_e32 v3, v3, v4, vcc
	v_cmp_class_f32_e32 vcc, v2, v227
	s_nop 1
	v_cndmask_b32_e32 v2, v3, v2, vcc
	v_div_scale_f32 v3, s[20:21], v2, v2, v141
	v_rcp_f32_e32 v4, v3
	s_nop 0
	v_fma_f32 v5, -v3, v4, 1.0
	v_fmac_f32_e32 v4, v5, v4
	v_div_scale_f32 v5, vcc, v141, v2, v141
	v_mul_f32_e32 v10, v5, v4
	v_fma_f32 v11, -v3, v10, v5
	v_fmac_f32_e32 v10, v11, v4
	v_fma_f32 v3, -v3, v10, v5
	v_div_fmas_f32 v3, v3, v4, v10
	v_div_fixup_f32 v26, v3, v2, v141
	v_mul_f32_e32 v0, v0, v26
	s_waitcnt vmcnt(0)
	v_mul_f32_e32 v0, v142, v0
	v_mul_f32_e32 v2, v12, v26
	v_mul_f32_e32 v2, v143, v2
	v_cvt_pk_bf16_f32 v12, v0, v2
	v_mul_f32_e32 v2, v14, v26
	v_mul_f32_e32 v0, v13, v26
	v_mul_f32_e32 v2, v145, v2
	v_mul_f32_e32 v0, v144, v0
	v_cvt_pk_bf16_f32 v13, v0, v2
	v_lshl_add_u64 v[2:3], v[224:225], 1, v[216:217]
	global_store_dwordx2 v[2:3], v[12:13], off
	v_mul_f32_e32 v0, v15, v26
	v_mul_f32_e32 v4, v64, v26
	v_mul_f32_e32 v5, v66, v26
	v_lshl_add_u64 v[12:13], v[222:223], 1, v[216:217]
	v_mul_f32_e32 v0, v146, v0
	v_mul_f32_e32 v4, v147, v4
	v_cvt_pk_bf16_f32 v4, v0, v4
	v_mul_f32_e32 v0, v65, v26
	v_mul_f32_e32 v5, v149, v5
	v_mul_f32_e32 v0, v148, v0
	v_cvt_pk_bf16_f32 v5, v0, v5
	global_store_dwordx2 v[12:13], v[4:5], off
	v_mul_f32_e32 v0, v67, v26
	v_mul_f32_e32 v4, v68, v26
	v_mul_f32_e32 v5, v70, v26
	v_mul_f32_e32 v0, v0, v150
	v_mul_f32_e32 v4, v4, v151
	v_cvt_pk_bf16_f32 v4, v0, v4
	v_mul_f32_e32 v0, v69, v26
	v_mul_f32_e32 v5, v5, v153
	v_mul_f32_e32 v0, v0, v152
	v_cvt_pk_bf16_f32 v5, v0, v5
	v_lshl_add_u64 v[12:13], v[220:221], 1, v[216:217]
	global_store_dwordx2 v[12:13], v[4:5], off
	v_mul_f32_e32 v0, v71, v26
	v_mul_f32_e32 v4, v72, v26
	v_mul_f32_e32 v5, v74, v26
	v_mul_f32_e32 v0, v0, v154
	v_mul_f32_e32 v4, v4, v155
	v_cvt_pk_bf16_f32 v4, v0, v4
	v_mul_f32_e32 v0, v73, v26
	v_mul_f32_e32 v5, v5, v157
	v_lshl_add_u64 v[12:13], v[218:219], 1, v[216:217]
	v_mul_f32_e32 v0, v0, v156
	v_cvt_pk_bf16_f32 v5, v0, v5
	global_store_dwordx2 v[12:13], v[4:5], off
	v_mul_f32_e32 v0, v48, v26
	v_mul_f32_e32 v4, v49, v26
	v_mul_f32_e32 v5, v51, v26
	v_mul_f32_e32 v0, v0, v158
	v_mul_f32_e32 v4, v4, v159
	v_cvt_pk_bf16_f32 v4, v0, v4
	v_mul_f32_e32 v0, v50, v26
	v_mul_f32_e32 v5, v5, v161
	v_mul_f32_e32 v0, v0, v160
	v_cvt_pk_bf16_f32 v5, v0, v5
	global_store_dwordx2 v[2:3], v[4:5], off offset:64
	v_mul_f32_e32 v0, v75, v26
	v_mul_f32_e32 v4, v52, v26
	v_mul_f32_e32 v5, v55, v26
	v_mul_f32_e32 v0, v0, v162
	v_mul_f32_e32 v4, v4, v163
	v_cvt_pk_bf16_f32 v4, v0, v4
	v_mul_f32_e32 v0, v76, v26
	v_mul_f32_e32 v5, v5, v165
	v_mul_f32_e32 v0, v0, v164
	v_cvt_pk_bf16_f32 v5, v0, v5
	global_store_dwordx2 v[2:3], v[4:5], off offset:80
	v_mul_f32_e32 v0, v54, v26
	v_mul_f32_e32 v4, v53, v26
	v_mul_f32_e32 v5, v56, v26
	v_mul_f32_e32 v0, v0, v166
	v_mul_f32_e32 v4, v4, v167
	v_cvt_pk_bf16_f32 v4, v0, v4
	v_mul_f32_e32 v0, v57, v26
	v_mul_f32_e32 v5, v5, v169
	v_mul_f32_e32 v0, v0, v168
	v_cvt_pk_bf16_f32 v5, v0, v5
	global_store_dwordx2 v[2:3], v[4:5], off offset:96
	v_mul_f32_e32 v0, v59, v26
	v_mul_f32_e32 v4, v58, v26
	v_mul_f32_e32 v5, v60, v26
	v_mul_f32_e32 v0, v0, v170
	v_mul_f32_e32 v4, v4, v171
	v_cvt_pk_bf16_f32 v4, v0, v4
	v_mul_f32_e32 v0, v62, v26
	v_mul_f32_e32 v5, v5, v173
	v_mul_f32_e32 v0, v0, v172
	v_cvt_pk_bf16_f32 v5, v0, v5
	global_store_dwordx2 v[2:3], v[4:5], off offset:112
	v_mul_f32_e32 v0, v61, v26
	v_mul_f32_e32 v4, v32, v26
	v_mul_f32_e32 v5, v33, v26
	v_mul_f32_e32 v0, v0, v174
	v_mul_f32_e32 v4, v4, v175
	v_cvt_pk_bf16_f32 v4, v0, v4
	v_mul_f32_e32 v0, v34, v26
	v_mul_f32_e32 v5, v5, v177
	v_mul_f32_e32 v0, v0, v176
	v_cvt_pk_bf16_f32 v5, v0, v5
	global_store_dwordx2 v[2:3], v[4:5], off offset:128
	v_mul_f32_e32 v0, v36, v26
	v_mul_f32_e32 v4, v35, v26
	v_mul_f32_e32 v5, v39, v26
	v_mul_f32_e32 v0, v0, v178
	v_mul_f32_e32 v4, v4, v179
	v_cvt_pk_bf16_f32 v4, v0, v4
	v_mul_f32_e32 v0, v63, v26
	v_mul_f32_e32 v5, v5, v181
	v_mul_f32_e32 v0, v0, v180
	v_cvt_pk_bf16_f32 v5, v0, v5
	global_store_dwordx2 v[2:3], v[4:5], off offset:144
	v_mul_f32_e32 v0, v38, v26
	v_mul_f32_e32 v4, v37, v26
	v_mul_f32_e32 v5, v40, v26
	v_mul_f32_e32 v0, v0, v182
	v_mul_f32_e32 v4, v4, v183
	v_cvt_pk_bf16_f32 v4, v0, v4
	v_mul_f32_e32 v0, v41, v26
	v_mul_f32_e32 v5, v5, v185
	v_mul_f32_e32 v0, v0, v184
	v_cvt_pk_bf16_f32 v5, v0, v5
	global_store_dwordx2 v[2:3], v[4:5], off offset:160
	v_mul_f32_e32 v0, v43, v26
	v_mul_f32_e32 v4, v42, v26
	v_mul_f32_e32 v5, v45, v26
	v_mul_f32_e32 v0, v0, v186
	v_mul_f32_e32 v4, v4, v187
	v_cvt_pk_bf16_f32 v4, v0, v4
	v_mul_f32_e32 v0, v46, v26
	v_mul_f32_e32 v5, v5, v189
	v_mul_f32_e32 v0, v0, v188
	v_cvt_pk_bf16_f32 v5, v0, v5
	global_store_dwordx2 v[2:3], v[4:5], off offset:176
	v_mul_f32_e32 v0, v44, v26
	v_mul_f32_e32 v4, v16, v26
	v_mul_f32_e32 v5, v17, v26
	v_mul_f32_e32 v0, v0, v190
	v_mul_f32_e32 v4, v4, v191
	v_cvt_pk_bf16_f32 v4, v0, v4
	v_mul_f32_e32 v0, v18, v26
	v_mul_f32_e32 v5, v5, v193
	v_mul_f32_e32 v0, v0, v192
	v_cvt_pk_bf16_f32 v5, v0, v5
	global_store_dwordx2 v[2:3], v[4:5], off offset:192
	v_mul_f32_e32 v0, v20, v26
	v_mul_f32_e32 v4, v19, v26
	v_mul_f32_e32 v5, v23, v26
	v_mul_f32_e32 v0, v0, v194
	v_mul_f32_e32 v4, v4, v195
	v_cvt_pk_bf16_f32 v4, v0, v4
	v_mul_f32_e32 v0, v47, v26
	v_mul_f32_e32 v5, v5, v197
	v_mul_f32_e32 v0, v0, v196
	v_cvt_pk_bf16_f32 v5, v0, v5
	global_store_dwordx2 v[2:3], v[4:5], off offset:208
	v_mul_f32_e32 v0, v22, v26
	v_mul_f32_e32 v4, v21, v26
	v_mul_f32_e32 v5, v24, v26
	v_mul_f32_e32 v0, v0, v198
	v_mul_f32_e32 v4, v4, v199
	v_cvt_pk_bf16_f32 v4, v0, v4
	v_mul_f32_e32 v0, v25, v26
	v_mul_f32_e32 v5, v5, v201
	v_mul_f32_e32 v0, v0, v200
	v_cvt_pk_bf16_f32 v5, v0, v5
	global_store_dwordx2 v[2:3], v[4:5], off offset:224
	v_mul_f32_e32 v0, v6, v26
	v_mul_f32_e32 v4, v7, v26
	v_mul_f32_e32 v5, v9, v26
	v_mul_f32_e32 v0, v0, v202
	v_mul_f32_e32 v4, v4, v203
	v_cvt_pk_bf16_f32 v4, v0, v4
	v_mul_f32_e32 v0, v8, v26
	v_mul_f32_e32 v5, v5, v205
	v_mul_f32_e32 v0, v0, v204
	v_cvt_pk_bf16_f32 v5, v0, v5
	global_store_dwordx2 v[2:3], v[4:5], off offset:240
	s_branch .LBB0_494
.LBB0_523:
	v_mov_b64_e32 v[208:209], 0x15ff
	v_mov_b64_e32 v[210:211], 0x1600
	v_mov_b64_e32 v[212:213], 0x400
	v_mov_b64_e32 v[214:215], 0x3ff
	v_readlane_b32 s0, v253, 10
	v_readlane_b32 s1, v253, 11
	s_mov_b64 s[10:11], 0
	s_and_b64 vcc, exec, s[0:1]
	s_cbranch_vccz .LBB0_525
	v_mov_b32_e32 v0, v206
	s_nop 0
	v_cmp_eq_u32_e32 vcc, 0, v0
	s_and_b64 s[10:11], vcc, exec

.LBB0_813:
	s_ashr_i32 s1, s61, 5
	s_mul_hi_i32 s11, s1, 0x9000
	s_mul_i32 s1, s1, 0x9000
	s_add_u32 s20, s50, s1
	s_addc_u32 s21, s51, s11
	v_lshl_add_u32 v50, s64, 8, v158
	v_ashrrev_i32_e32 v51, 31, v50
	v_lshlrev_b64 v[50:51], 2, v[50:51]
	v_lshl_add_u64 v[52:53], s[20:21], 0, v[50:51]
	s_mov_b64 s[20:21], -1
	s_andn2_b64 vcc, exec, s[44:45]
	global_load_dwordx4 v[100:103], v[52:53], off
	global_load_dwordx4 v[152:155], v[52:53], off offset:64
	global_load_dwordx4 v[160:163], v[52:53], off offset:512
	global_load_dwordx4 v[164:167], v[52:53], off offset:576
	v_lshl_add_u32 v104, s61, 8, v156
	v_mov_b32_e32 v86, v104
	v_ashrrev_i32_e32 v87, 31, v86
	v_lshlrev_b64 v[86:87], 12, v[86:87]
	v_lshl_add_u64 v[86:87], v[86:87], 0, v[50:51]
	v_lshl_add_u64 v[88:89], s[48:49], 0, v[86:87]
	global_load_dwordx4 v[168:171], v[88:89], off
	global_load_dwordx4 v[172:175], v[88:89], off offset:64
	global_load_dwordx4 v[176:179], v[88:89], off offset:512
	global_load_dwordx4 v[180:183], v[88:89], off offset:576
	v_add_u32_e32 v86, 16, v104
	v_ashrrev_i32_e32 v87, 31, v86
	v_lshlrev_b64 v[86:87], 12, v[86:87]
	v_lshl_add_u64 v[86:87], v[86:87], 0, v[50:51]
	v_lshl_add_u64 v[88:89], s[48:49], 0, v[86:87]
	global_load_dwordx4 v[184:187], v[88:89], off
	global_load_dwordx4 v[188:191], v[88:89], off offset:64
	global_load_dwordx4 v[192:195], v[88:89], off offset:512
	global_load_dwordx4 v[196:199], v[88:89], off offset:576
	s_waitcnt vmcnt(4)
	v_pk_fma_f32 v[142:143], v[142:143], v[100:101], v[168:169]
	v_pk_fma_f32 v[144:145], v[144:145], v[102:103], v[170:171]
	v_pk_fma_f32 v[138:139], v[138:139], v[152:153], v[172:173]
	v_pk_fma_f32 v[140:141], v[140:141], v[154:155], v[174:175]
	v_pk_fma_f32 v[134:135], v[134:135], v[160:161], v[176:177]
	v_pk_fma_f32 v[136:137], v[136:137], v[162:163], v[178:179]
	v_pk_fma_f32 v[130:131], v[130:131], v[164:165], v[180:181]
	v_pk_fma_f32 v[132:133], v[132:133], v[166:167], v[182:183]
	v_mov_b32_e32 v86, v104
	v_ashrrev_i32_e32 v87, 31, v86
	v_lshlrev_b64 v[86:87], 12, v[86:87]
	v_lshl_add_u64 v[86:87], v[86:87], 0, v[50:51]
	v_lshl_add_u64 v[98:99], s[48:49], 0, v[86:87]
	global_store_dwordx4 v[98:99], v[142:145], off
	global_store_dwordx4 v[98:99], v[138:141], off offset:64
	global_store_dwordx4 v[98:99], v[134:137], off offset:512
	global_store_dwordx4 v[98:99], v[130:133], off offset:576
	s_nop 1
	v_add_u32_e32 v86, 32, v104
	v_ashrrev_i32_e32 v87, 31, v86
	v_lshlrev_b64 v[86:87], 12, v[86:87]
	v_lshl_add_u64 v[86:87], v[86:87], 0, v[50:51]
	v_lshl_add_u64 v[88:89], s[48:49], 0, v[86:87]
	global_load_dwordx4 v[200:203], v[88:89], off
	global_load_dwordx4 v[168:171], v[88:89], off offset:64
	global_load_dwordx4 v[172:175], v[88:89], off offset:512
	global_load_dwordx4 v[176:179], v[88:89], off offset:576
	v_add_u32_e32 v86, 48, v104
	v_ashrrev_i32_e32 v87, 31, v86
	v_lshlrev_b64 v[86:87], 12, v[86:87]
	v_lshl_add_u64 v[86:87], v[86:87], 0, v[50:51]
	v_lshl_add_u64 v[88:89], s[48:49], 0, v[86:87]
	global_load_dwordx4 v[180:183], v[88:89], off
	global_load_dwordx4 v[142:145], v[88:89], off offset:64
	global_load_dwordx4 v[138:141], v[88:89], off offset:512
	global_load_dwordx4 v[134:137], v[88:89], off offset:576
	s_waitcnt vmcnt(12)
	v_pk_fma_f32 v[126:127], v[126:127], v[100:101], v[184:185]
	v_pk_fma_f32 v[128:129], v[128:129], v[102:103], v[186:187]
	v_pk_fma_f32 v[122:123], v[122:123], v[152:153], v[188:189]
	v_pk_fma_f32 v[124:125], v[124:125], v[154:155], v[190:191]
	v_pk_fma_f32 v[118:119], v[118:119], v[160:161], v[192:193]
	v_pk_fma_f32 v[120:121], v[120:121], v[162:163], v[194:195]
	v_pk_fma_f32 v[114:115], v[114:115], v[164:165], v[196:197]
	v_pk_fma_f32 v[116:117], v[116:117], v[166:167], v[198:199]
	v_add_u32_e32 v86, 16, v104
	v_ashrrev_i32_e32 v87, 31, v86
	v_lshlrev_b64 v[86:87], 12, v[86:87]
	v_lshl_add_u64 v[86:87], v[86:87], 0, v[50:51]
	v_lshl_add_u64 v[98:99], s[48:49], 0, v[86:87]
	global_store_dwordx4 v[98:99], v[126:129], off
	global_store_dwordx4 v[98:99], v[122:125], off offset:64
	global_store_dwordx4 v[98:99], v[118:121], off offset:512
	global_store_dwordx4 v[98:99], v[114:117], off offset:576
	s_nop 1
	v_add_u32_e32 v86, 0x80, v104
	v_ashrrev_i32_e32 v87, 31, v86
	v_lshlrev_b64 v[86:87], 12, v[86:87]
	v_lshl_add_u64 v[86:87], v[86:87], 0, v[50:51]
	v_lshl_add_u64 v[88:89], s[48:49], 0, v[86:87]
	global_load_dwordx4 v[130:133], v[88:89], off
	global_load_dwordx4 v[184:187], v[88:89], off offset:64
	global_load_dwordx4 v[188:191], v[88:89], off offset:512
	global_load_dwordx4 v[192:195], v[88:89], off offset:576
	v_add_u32_e32 v86, 0x90, v104
	v_ashrrev_i32_e32 v87, 31, v86
	v_lshlrev_b64 v[86:87], 12, v[86:87]
	v_lshl_add_u64 v[86:87], v[86:87], 0, v[50:51]
	v_lshl_add_u64 v[88:89], s[48:49], 0, v[86:87]
	global_load_dwordx4 v[196:199], v[88:89], off
	global_load_dwordx4 v[126:129], v[88:89], off offset:64
	global_load_dwordx4 v[122:125], v[88:89], off offset:512
	global_load_dwordx4 v[118:121], v[88:89], off offset:576
	s_waitcnt vmcnt(16)
	v_pk_fma_f32 v[110:111], v[110:111], v[100:101], v[200:201]
	v_pk_fma_f32 v[112:113], v[112:113], v[102:103], v[202:203]
	v_pk_fma_f32 v[106:107], v[106:107], v[152:153], v[168:169]
	v_pk_fma_f32 v[108:109], v[108:109], v[154:155], v[170:171]
	v_pk_fma_f32 v[94:95], v[94:95], v[160:161], v[172:173]
	v_pk_fma_f32 v[96:97], v[96:97], v[162:163], v[174:175]
	v_pk_fma_f32 v[90:91], v[90:91], v[164:165], v[176:177]
	v_pk_fma_f32 v[92:93], v[92:93], v[166:167], v[178:179]
	v_add_u32_e32 v86, 32, v104
	v_ashrrev_i32_e32 v87, 31, v86
	v_lshlrev_b64 v[86:87], 12, v[86:87]
	v_lshl_add_u64 v[86:87], v[86:87], 0, v[50:51]
	v_lshl_add_u64 v[98:99], s[48:49], 0, v[86:87]
	global_store_dwordx4 v[98:99], v[110:113], off
	global_store_dwordx4 v[98:99], v[106:109], off offset:64
	global_store_dwordx4 v[98:99], v[94:97], off offset:512
	global_store_dwordx4 v[98:99], v[90:93], off offset:576
	s_nop 1
	v_add_u32_e32 v86, 0xa0, v104
	v_ashrrev_i32_e32 v87, 31, v86
	v_lshlrev_b64 v[86:87], 12, v[86:87]
	v_lshl_add_u64 v[86:87], v[86:87], 0, v[50:51]
	v_lshl_add_u64 v[88:89], s[48:49], 0, v[86:87]
	global_load_dwordx4 v[114:117], v[88:89], off
	global_load_dwordx4 v[200:203], v[88:89], off offset:64
	global_load_dwordx4 v[168:171], v[88:89], off offset:512
	global_load_dwordx4 v[172:175], v[88:89], off offset:576
	v_add_u32_e32 v86, 0xb0, v104
	v_ashrrev_i32_e32 v87, 31, v86
	v_lshlrev_b64 v[86:87], 12, v[86:87]
	v_lshl_add_u64 v[86:87], v[86:87], 0, v[50:51]
	v_lshl_add_u64 v[88:89], s[48:49], 0, v[86:87]
	global_load_dwordx4 v[176:179], v[88:89], off
	global_load_dwordx4 v[110:113], v[88:89], off offset:64
	global_load_dwordx4 v[106:109], v[88:89], off offset:512
	global_load_dwordx4 v[94:97], v[88:89], off offset:576
	s_waitcnt vmcnt(24)
	v_pk_fma_f32 v[82:83], v[82:83], v[100:101], v[180:181]
	v_pk_fma_f32 v[84:85], v[84:85], v[102:103], v[182:183]
	v_pk_fma_f32 v[78:79], v[78:79], v[152:153], v[142:143]
	v_pk_fma_f32 v[80:81], v[80:81], v[154:155], v[144:145]
	v_pk_fma_f32 v[74:75], v[74:75], v[160:161], v[138:139]
	v_pk_fma_f32 v[76:77], v[76:77], v[162:163], v[140:141]
	v_pk_fma_f32 v[70:71], v[70:71], v[164:165], v[134:135]
	v_pk_fma_f32 v[72:73], v[72:73], v[166:167], v[136:137]
	v_add_u32_e32 v86, 48, v104
	v_ashrrev_i32_e32 v87, 31, v86
	v_lshlrev_b64 v[86:87], 12, v[86:87]
	v_lshl_add_u64 v[86:87], v[86:87], 0, v[50:51]
	v_lshl_add_u64 v[98:99], s[48:49], 0, v[86:87]
	global_store_dwordx4 v[98:99], v[82:85], off
	global_store_dwordx4 v[98:99], v[78:81], off offset:64
	global_store_dwordx4 v[98:99], v[74:77], off offset:512
	global_store_dwordx4 v[98:99], v[70:73], off offset:576
	s_waitcnt vmcnt(20)
	v_pk_fma_f32 v[66:67], v[66:67], v[100:101], v[130:131]
	v_pk_fma_f32 v[68:69], v[68:69], v[102:103], v[132:133]
	v_pk_fma_f32 v[62:63], v[62:63], v[152:153], v[184:185]
	v_pk_fma_f32 v[64:65], v[64:65], v[154:155], v[186:187]
	v_pk_fma_f32 v[58:59], v[58:59], v[160:161], v[188:189]
	v_pk_fma_f32 v[60:61], v[60:61], v[162:163], v[190:191]
	v_pk_fma_f32 v[54:55], v[54:55], v[164:165], v[192:193]
	v_pk_fma_f32 v[56:57], v[56:57], v[166:167], v[194:195]
	v_add_u32_e32 v86, 0x80, v104
	v_ashrrev_i32_e32 v87, 31, v86
	v_lshlrev_b64 v[86:87], 12, v[86:87]
	v_lshl_add_u64 v[86:87], v[86:87], 0, v[50:51]
	v_lshl_add_u64 v[98:99], s[48:49], 0, v[86:87]
	global_store_dwordx4 v[98:99], v[66:69], off
	global_store_dwordx4 v[98:99], v[62:65], off offset:64
	global_store_dwordx4 v[98:99], v[58:61], off offset:512
	global_store_dwordx4 v[98:99], v[54:57], off offset:576
	s_waitcnt vmcnt(20)
	v_pk_fma_f32 v[46:47], v[46:47], v[100:101], v[196:197]
	v_pk_fma_f32 v[48:49], v[48:49], v[102:103], v[198:199]
	v_pk_fma_f32 v[42:43], v[42:43], v[152:153], v[126:127]
	v_pk_fma_f32 v[44:45], v[44:45], v[154:155], v[128:129]
	v_pk_fma_f32 v[38:39], v[38:39], v[160:161], v[122:123]
	v_pk_fma_f32 v[40:41], v[40:41], v[162:163], v[124:125]
	v_pk_fma_f32 v[34:35], v[34:35], v[164:165], v[118:119]
	v_pk_fma_f32 v[36:37], v[36:37], v[166:167], v[120:121]
	v_add_u32_e32 v86, 0x90, v104
	v_ashrrev_i32_e32 v87, 31, v86
	v_lshlrev_b64 v[86:87], 12, v[86:87]
	v_lshl_add_u64 v[86:87], v[86:87], 0, v[50:51]
	v_lshl_add_u64 v[98:99], s[48:49], 0, v[86:87]
	global_store_dwordx4 v[98:99], v[46:49], off
	global_store_dwordx4 v[98:99], v[42:45], off offset:64
	global_store_dwordx4 v[98:99], v[38:41], off offset:512
	global_store_dwordx4 v[98:99], v[34:37], off offset:576
	s_waitcnt vmcnt(16)
	v_pk_fma_f32 v[30:31], v[30:31], v[100:101], v[114:115]
	v_pk_fma_f32 v[32:33], v[32:33], v[102:103], v[116:117]
	v_pk_fma_f32 v[26:27], v[26:27], v[152:153], v[200:201]
	v_pk_fma_f32 v[28:29], v[28:29], v[154:155], v[202:203]
	v_pk_fma_f32 v[22:23], v[22:23], v[160:161], v[168:169]
	v_pk_fma_f32 v[24:25], v[24:25], v[162:163], v[170:171]
	v_pk_fma_f32 v[18:19], v[18:19], v[164:165], v[172:173]
	v_pk_fma_f32 v[20:21], v[20:21], v[166:167], v[174:175]
	v_add_u32_e32 v86, 0xa0, v104
	v_ashrrev_i32_e32 v87, 31, v86
	v_lshlrev_b64 v[86:87], 12, v[86:87]
	v_lshl_add_u64 v[86:87], v[86:87], 0, v[50:51]
	v_lshl_add_u64 v[98:99], s[48:49], 0, v[86:87]
	global_store_dwordx4 v[98:99], v[30:33], off
	global_store_dwordx4 v[98:99], v[26:29], off offset:64
	global_store_dwordx4 v[98:99], v[22:25], off offset:512
	global_store_dwordx4 v[98:99], v[18:21], off offset:576
	s_waitcnt vmcnt(16)
	v_pk_fma_f32 v[14:15], v[14:15], v[100:101], v[176:177]
	v_pk_fma_f32 v[16:17], v[16:17], v[102:103], v[178:179]
	v_pk_fma_f32 v[10:11], v[10:11], v[152:153], v[110:111]
	v_pk_fma_f32 v[12:13], v[12:13], v[154:155], v[112:113]
	v_pk_fma_f32 v[6:7], v[6:7], v[160:161], v[106:107]
	v_pk_fma_f32 v[8:9], v[8:9], v[162:163], v[108:109]
	v_pk_fma_f32 v[2:3], v[2:3], v[164:165], v[94:95]
	v_pk_fma_f32 v[4:5], v[4:5], v[166:167], v[96:97]
	v_add_u32_e32 v86, 0xb0, v104
	v_ashrrev_i32_e32 v87, 31, v86
	v_lshlrev_b64 v[86:87], 12, v[86:87]
	v_lshl_add_u64 v[86:87], v[86:87], 0, v[50:51]
	v_lshl_add_u64 v[98:99], s[48:49], 0, v[86:87]
	global_store_dwordx4 v[98:99], v[14:17], off
	global_store_dwordx4 v[98:99], v[10:13], off offset:64
	global_store_dwordx4 v[98:99], v[6:9], off offset:512
	global_store_dwordx4 v[98:99], v[2:5], off offset:576
	s_cbranch_vccnz .LBB0_806
	s_and_b64 vcc, exec, s[38:39]
	s_cbranch_vccnz .LBB0_805
	s_barrier
	s_branch .LBB0_805

.LBB0_947:
	v_mul_f32_e32 v152, 0xbfb8aa3b, v126
	v_mul_f32_e32 v153, 0xbfb8aa3b, v127
	v_mul_f32_e32 v154, 0xbfb8aa3b, v128
	v_mul_f32_e32 v155, 0xbfb8aa3b, v129
	v_mul_f32_e32 v156, 0xbfb8aa3b, v118
	v_mul_f32_e32 v157, 0xbfb8aa3b, v119
	v_mul_f32_e32 v158, 0xbfb8aa3b, v120
	v_mul_f32_e32 v159, 0xbfb8aa3b, v121
	v_exp_f32_e32 v152, v152
	v_exp_f32_e32 v153, v153
	v_exp_f32_e32 v154, v154
	v_exp_f32_e32 v155, v155
	v_exp_f32_e32 v156, v156
	v_exp_f32_e32 v157, v157
	v_exp_f32_e32 v158, v158
	v_exp_f32_e32 v159, v159
	v_add_f32_e32 v152, 1.0, v152
	v_add_f32_e32 v153, 1.0, v153
	v_add_f32_e32 v154, 1.0, v154
	v_add_f32_e32 v155, 1.0, v155
	v_add_f32_e32 v156, 1.0, v156
	v_add_f32_e32 v157, 1.0, v157
	v_add_f32_e32 v158, 1.0, v158
	v_add_f32_e32 v159, 1.0, v159
	v_rcp_f32_e32 v152, v152
	v_rcp_f32_e32 v153, v153
	v_rcp_f32_e32 v154, v154
	v_rcp_f32_e32 v155, v155
	v_rcp_f32_e32 v156, v156
	v_rcp_f32_e32 v157, v157
	v_rcp_f32_e32 v158, v158
	v_rcp_f32_e32 v159, v159
	v_mul_f32_e32 v152, v126, v152
	v_mul_f32_e32 v153, v127, v153
	v_mul_f32_e32 v154, v128, v154
	v_mul_f32_e32 v155, v129, v155
	v_mul_f32_e32 v156, v118, v156
	v_mul_f32_e32 v157, v119, v157
	v_mul_f32_e32 v158, v120, v158
	v_mul_f32_e32 v159, v121, v159
	v_mul_f32_e32 v152, v152, v122
	v_mul_f32_e32 v153, v153, v123
	v_mul_f32_e32 v154, v154, v124
	v_mul_f32_e32 v155, v155, v125
	v_mul_f32_e32 v156, v156, v114
	v_mul_f32_e32 v157, v157, v115
	v_mul_f32_e32 v158, v158, v116
	v_mul_f32_e32 v159, v159, v117
	v_cvt_pk_bf16_f32 v160, v152, v153
	v_cvt_pk_bf16_f32 v161, v154, v155
	v_cvt_pk_bf16_f32 v162, v156, v157
	v_cvt_pk_bf16_f32 v163, v158, v159
	v_lshl_add_u32 v148, s57, 7, v144
	v_lshl_add_u32 v146, s58, 8, v142
	v_ashrrev_i32_e32 v149, 31, v148
	v_mov_b64_e32 v[140:141], s[0:1]
	v_mad_i64_i32 v[150:151], s[20:21], v146, s62, v[140:141]
	v_readlane_b32 s60, v255, 0
	s_nop 1
	s_andn2_b64 vcc, exec, s[40:41]
	v_readlane_b32 s61, v255, 1
	s_nop 1
	v_lshlrev_b64 v[114:115], 1, v[148:149]
	v_lshl_add_u64 v[120:121], v[150:151], 0, v[114:115]
	global_store_dwordx4 v[120:121], v[160:163], off
	v_mul_f32_e32 v152, 0xbfb8aa3b, v110
	v_mul_f32_e32 v153, 0xbfb8aa3b, v111
	v_mul_f32_e32 v154, 0xbfb8aa3b, v112
	v_mul_f32_e32 v155, 0xbfb8aa3b, v113
	v_mul_f32_e32 v156, 0xbfb8aa3b, v102
	v_mul_f32_e32 v157, 0xbfb8aa3b, v103
	v_mul_f32_e32 v158, 0xbfb8aa3b, v104
	v_mul_f32_e32 v159, 0xbfb8aa3b, v105
	v_exp_f32_e32 v152, v152
	v_exp_f32_e32 v153, v153
	v_exp_f32_e32 v154, v154
	v_exp_f32_e32 v155, v155
	v_exp_f32_e32 v156, v156
	v_exp_f32_e32 v157, v157
	v_exp_f32_e32 v158, v158
	v_exp_f32_e32 v159, v159
	v_add_f32_e32 v152, 1.0, v152
	v_add_f32_e32 v153, 1.0, v153
	v_add_f32_e32 v154, 1.0, v154
	v_add_f32_e32 v155, 1.0, v155
	v_add_f32_e32 v156, 1.0, v156
	v_add_f32_e32 v157, 1.0, v157
	v_add_f32_e32 v158, 1.0, v158
	v_add_f32_e32 v159, 1.0, v159
	v_rcp_f32_e32 v152, v152
	v_rcp_f32_e32 v153, v153
	v_rcp_f32_e32 v154, v154
	v_rcp_f32_e32 v155, v155
	v_rcp_f32_e32 v156, v156
	v_rcp_f32_e32 v157, v157
	v_rcp_f32_e32 v158, v158
	v_rcp_f32_e32 v159, v159
	v_mul_f32_e32 v152, v110, v152
	v_mul_f32_e32 v153, v111, v153
	v_mul_f32_e32 v154, v112, v154
	v_mul_f32_e32 v155, v113, v155
	v_mul_f32_e32 v156, v102, v156
	v_mul_f32_e32 v157, v103, v157
	v_mul_f32_e32 v158, v104, v158
	v_mul_f32_e32 v159, v105, v159
	v_mul_f32_e32 v152, v152, v106
	v_mul_f32_e32 v153, v153, v107
	v_mul_f32_e32 v154, v154, v108
	v_mul_f32_e32 v155, v155, v109
	v_mul_f32_e32 v156, v156, v98
	v_mul_f32_e32 v157, v157, v99
	v_mul_f32_e32 v158, v158, v100
	v_mul_f32_e32 v159, v159, v101
	v_cvt_pk_bf16_f32 v160, v152, v153
	v_cvt_pk_bf16_f32 v161, v154, v155
	v_cvt_pk_bf16_f32 v162, v156, v157
	v_cvt_pk_bf16_f32 v163, v158, v159
	v_or_b32_e32 v116, 16, v146
	v_mad_i64_i32 v[116:117], s[20:21], v116, s62, v[140:141]
	v_lshl_add_u64 v[102:103], v[116:117], 0, v[114:115]
	global_store_dwordx4 v[102:103], v[160:163], off
	v_mul_f32_e32 v152, 0xbfb8aa3b, v94
	v_mul_f32_e32 v153, 0xbfb8aa3b, v95
	v_mul_f32_e32 v154, 0xbfb8aa3b, v96
	v_mul_f32_e32 v155, 0xbfb8aa3b, v97
	v_mul_f32_e32 v156, 0xbfb8aa3b, v86
	v_mul_f32_e32 v157, 0xbfb8aa3b, v87
	v_mul_f32_e32 v158, 0xbfb8aa3b, v88
	v_mul_f32_e32 v159, 0xbfb8aa3b, v89
	v_exp_f32_e32 v152, v152
	v_exp_f32_e32 v153, v153
	v_exp_f32_e32 v154, v154
	v_exp_f32_e32 v155, v155
	v_exp_f32_e32 v156, v156
	v_exp_f32_e32 v157, v157
	v_exp_f32_e32 v158, v158
	v_exp_f32_e32 v159, v159
	v_add_f32_e32 v152, 1.0, v152
	v_add_f32_e32 v153, 1.0, v153
	v_add_f32_e32 v154, 1.0, v154
	v_add_f32_e32 v155, 1.0, v155
	v_add_f32_e32 v156, 1.0, v156
	v_add_f32_e32 v157, 1.0, v157
	v_add_f32_e32 v158, 1.0, v158
	v_add_f32_e32 v159, 1.0, v159
	v_rcp_f32_e32 v152, v152
	v_rcp_f32_e32 v153, v153
	v_rcp_f32_e32 v154, v154
	v_rcp_f32_e32 v155, v155
	v_rcp_f32_e32 v156, v156
	v_rcp_f32_e32 v157, v157
	v_rcp_f32_e32 v158, v158
	v_rcp_f32_e32 v159, v159
	v_mul_f32_e32 v152, v94, v152
	v_mul_f32_e32 v153, v95, v153
	v_mul_f32_e32 v154, v96, v154
	v_mul_f32_e32 v155, v97, v155
	v_mul_f32_e32 v156, v86, v156
	v_mul_f32_e32 v157, v87, v157
	v_mul_f32_e32 v158, v88, v158
	v_mul_f32_e32 v159, v89, v159
	v_mul_f32_e32 v152, v152, v90
	v_mul_f32_e32 v153, v153, v91
	v_mul_f32_e32 v154, v154, v92
	v_mul_f32_e32 v155, v155, v93
	v_mul_f32_e32 v156, v156, v82
	v_mul_f32_e32 v157, v157, v83
	v_mul_f32_e32 v158, v158, v84
	v_mul_f32_e32 v159, v159, v85
	v_cvt_pk_bf16_f32 v160, v152, v153
	v_cvt_pk_bf16_f32 v161, v154, v155
	v_cvt_pk_bf16_f32 v162, v156, v157
	v_cvt_pk_bf16_f32 v163, v158, v159
	v_or_b32_e32 v98, 32, v146
	v_mad_i64_i32 v[98:99], s[20:21], v98, s62, v[140:141]
	v_lshl_add_u64 v[86:87], v[98:99], 0, v[114:115]
	global_store_dwordx4 v[86:87], v[160:163], off
	v_mul_f32_e32 v152, 0xbfb8aa3b, v78
	v_mul_f32_e32 v153, 0xbfb8aa3b, v79
	v_mul_f32_e32 v154, 0xbfb8aa3b, v80
	v_mul_f32_e32 v155, 0xbfb8aa3b, v81
	v_mul_f32_e32 v156, 0xbfb8aa3b, v70
	v_mul_f32_e32 v157, 0xbfb8aa3b, v71
	v_mul_f32_e32 v158, 0xbfb8aa3b, v72
	v_mul_f32_e32 v159, 0xbfb8aa3b, v73
	v_exp_f32_e32 v152, v152
	v_exp_f32_e32 v153, v153
	v_exp_f32_e32 v154, v154
	v_exp_f32_e32 v155, v155
	v_exp_f32_e32 v156, v156
	v_exp_f32_e32 v157, v157
	v_exp_f32_e32 v158, v158
	v_exp_f32_e32 v159, v159
	v_add_f32_e32 v152, 1.0, v152
	v_add_f32_e32 v153, 1.0, v153
	v_add_f32_e32 v154, 1.0, v154
	v_add_f32_e32 v155, 1.0, v155
	v_add_f32_e32 v156, 1.0, v156
	v_add_f32_e32 v157, 1.0, v157
	v_add_f32_e32 v158, 1.0, v158
	v_add_f32_e32 v159, 1.0, v159
	v_rcp_f32_e32 v152, v152
	v_rcp_f32_e32 v153, v153
	v_rcp_f32_e32 v154, v154
	v_rcp_f32_e32 v155, v155
	v_rcp_f32_e32 v156, v156
	v_rcp_f32_e32 v157, v157
	v_rcp_f32_e32 v158, v158
	v_rcp_f32_e32 v159, v159
	v_mul_f32_e32 v152, v78, v152
	v_mul_f32_e32 v153, v79, v153
	v_mul_f32_e32 v154, v80, v154
	v_mul_f32_e32 v155, v81, v155
	v_mul_f32_e32 v156, v70, v156
	v_mul_f32_e32 v157, v71, v157
	v_mul_f32_e32 v158, v72, v158
	v_mul_f32_e32 v159, v73, v159
	v_mul_f32_e32 v152, v152, v74
	v_mul_f32_e32 v153, v153, v75
	v_mul_f32_e32 v154, v154, v76
	v_mul_f32_e32 v155, v155, v77
	v_mul_f32_e32 v156, v156, v66
	v_mul_f32_e32 v157, v157, v67
	v_mul_f32_e32 v158, v158, v68
	v_mul_f32_e32 v159, v159, v69
	v_cvt_pk_bf16_f32 v160, v152, v153
	v_cvt_pk_bf16_f32 v161, v154, v155
	v_cvt_pk_bf16_f32 v162, v156, v157
	v_cvt_pk_bf16_f32 v163, v158, v159
	v_or_b32_e32 v82, 48, v146
	v_mad_i64_i32 v[82:83], s[20:21], v82, s62, v[140:141]
	v_lshl_add_u64 v[70:71], v[82:83], 0, v[114:115]
	global_store_dwordx4 v[70:71], v[160:163], off
	v_mul_f32_e32 v152, 0xbfb8aa3b, v62
	v_mul_f32_e32 v153, 0xbfb8aa3b, v63
	v_mul_f32_e32 v154, 0xbfb8aa3b, v64
	v_mul_f32_e32 v155, 0xbfb8aa3b, v65
	v_mul_f32_e32 v156, 0xbfb8aa3b, v54
	v_mul_f32_e32 v157, 0xbfb8aa3b, v55
	v_mul_f32_e32 v158, 0xbfb8aa3b, v56
	v_mul_f32_e32 v159, 0xbfb8aa3b, v57
	v_exp_f32_e32 v152, v152
	v_exp_f32_e32 v153, v153
	v_exp_f32_e32 v154, v154
	v_exp_f32_e32 v155, v155
	v_exp_f32_e32 v156, v156
	v_exp_f32_e32 v157, v157
	v_exp_f32_e32 v158, v158
	v_exp_f32_e32 v159, v159
	v_add_f32_e32 v152, 1.0, v152
	v_add_f32_e32 v153, 1.0, v153
	v_add_f32_e32 v154, 1.0, v154
	v_add_f32_e32 v155, 1.0, v155
	v_add_f32_e32 v156, 1.0, v156
	v_add_f32_e32 v157, 1.0, v157
	v_add_f32_e32 v158, 1.0, v158
	v_add_f32_e32 v159, 1.0, v159
	v_rcp_f32_e32 v152, v152
	v_rcp_f32_e32 v153, v153
	v_rcp_f32_e32 v154, v154
	v_rcp_f32_e32 v155, v155
	v_rcp_f32_e32 v156, v156
	v_rcp_f32_e32 v157, v157
	v_rcp_f32_e32 v158, v158
	v_rcp_f32_e32 v159, v159
	v_mul_f32_e32 v152, v62, v152
	v_mul_f32_e32 v153, v63, v153
	v_mul_f32_e32 v154, v64, v154
	v_mul_f32_e32 v155, v65, v155
	v_mul_f32_e32 v156, v54, v156
	v_mul_f32_e32 v157, v55, v157
	v_mul_f32_e32 v158, v56, v158
	v_mul_f32_e32 v159, v57, v159
	v_mul_f32_e32 v152, v152, v58
	v_mul_f32_e32 v153, v153, v59
	v_mul_f32_e32 v154, v154, v60
	v_mul_f32_e32 v155, v155, v61
	v_mul_f32_e32 v156, v156, v50
	v_mul_f32_e32 v157, v157, v51
	v_mul_f32_e32 v158, v158, v52
	v_mul_f32_e32 v159, v159, v53
	v_cvt_pk_bf16_f32 v160, v152, v153
	v_cvt_pk_bf16_f32 v161, v154, v155
	v_cvt_pk_bf16_f32 v162, v156, v157
	v_cvt_pk_bf16_f32 v163, v158, v159
	v_add_u32_e32 v66, 0x80, v146
	v_mad_i64_i32 v[66:67], s[20:21], v66, s62, v[140:141]
	v_lshl_add_u64 v[54:55], v[66:67], 0, v[114:115]
	global_store_dwordx4 v[54:55], v[160:163], off
	v_mul_f32_e32 v152, 0xbfb8aa3b, v46
	v_mul_f32_e32 v153, 0xbfb8aa3b, v47
	v_mul_f32_e32 v154, 0xbfb8aa3b, v48
	v_mul_f32_e32 v155, 0xbfb8aa3b, v49
	v_mul_f32_e32 v156, 0xbfb8aa3b, v38
	v_mul_f32_e32 v157, 0xbfb8aa3b, v39
	v_mul_f32_e32 v158, 0xbfb8aa3b, v40
	v_mul_f32_e32 v159, 0xbfb8aa3b, v41
	v_exp_f32_e32 v152, v152
	v_exp_f32_e32 v153, v153
	v_exp_f32_e32 v154, v154
	v_exp_f32_e32 v155, v155
	v_exp_f32_e32 v156, v156
	v_exp_f32_e32 v157, v157
	v_exp_f32_e32 v158, v158
	v_exp_f32_e32 v159, v159
	v_add_f32_e32 v152, 1.0, v152
	v_add_f32_e32 v153, 1.0, v153
	v_add_f32_e32 v154, 1.0, v154
	v_add_f32_e32 v155, 1.0, v155
	v_add_f32_e32 v156, 1.0, v156
	v_add_f32_e32 v157, 1.0, v157
	v_add_f32_e32 v158, 1.0, v158
	v_add_f32_e32 v159, 1.0, v159
	v_rcp_f32_e32 v152, v152
	v_rcp_f32_e32 v153, v153
	v_rcp_f32_e32 v154, v154
	v_rcp_f32_e32 v155, v155
	v_rcp_f32_e32 v156, v156
	v_rcp_f32_e32 v157, v157
	v_rcp_f32_e32 v158, v158
	v_rcp_f32_e32 v159, v159
	v_mul_f32_e32 v152, v46, v152
	v_mul_f32_e32 v153, v47, v153
	v_mul_f32_e32 v154, v48, v154
	v_mul_f32_e32 v155, v49, v155
	v_mul_f32_e32 v156, v38, v156
	v_mul_f32_e32 v157, v39, v157
	v_mul_f32_e32 v158, v40, v158
	v_mul_f32_e32 v159, v41, v159
	v_mul_f32_e32 v152, v152, v42
	v_mul_f32_e32 v153, v153, v43
	v_mul_f32_e32 v154, v154, v44
	v_mul_f32_e32 v155, v155, v45
	v_mul_f32_e32 v156, v156, v34
	v_mul_f32_e32 v157, v157, v35
	v_mul_f32_e32 v158, v158, v36
	v_mul_f32_e32 v159, v159, v37
	v_cvt_pk_bf16_f32 v160, v152, v153
	v_cvt_pk_bf16_f32 v161, v154, v155
	v_cvt_pk_bf16_f32 v162, v156, v157
	v_cvt_pk_bf16_f32 v163, v158, v159
	v_add_u32_e32 v50, 0x90, v146
	v_mad_i64_i32 v[50:51], s[20:21], v50, s62, v[140:141]
	v_lshl_add_u64 v[38:39], v[50:51], 0, v[114:115]
	global_store_dwordx4 v[38:39], v[160:163], off
	v_mul_f32_e32 v152, 0xbfb8aa3b, v30
	v_mul_f32_e32 v153, 0xbfb8aa3b, v31
	v_mul_f32_e32 v154, 0xbfb8aa3b, v32
	v_mul_f32_e32 v155, 0xbfb8aa3b, v33
	v_mul_f32_e32 v156, 0xbfb8aa3b, v22
	v_mul_f32_e32 v157, 0xbfb8aa3b, v23
	v_mul_f32_e32 v158, 0xbfb8aa3b, v24
	v_mul_f32_e32 v159, 0xbfb8aa3b, v25
	v_exp_f32_e32 v152, v152
	v_exp_f32_e32 v153, v153
	v_exp_f32_e32 v154, v154
	v_exp_f32_e32 v155, v155
	v_exp_f32_e32 v156, v156
	v_exp_f32_e32 v157, v157
	v_exp_f32_e32 v158, v158
	v_exp_f32_e32 v159, v159
	v_add_f32_e32 v152, 1.0, v152
	v_add_f32_e32 v153, 1.0, v153
	v_add_f32_e32 v154, 1.0, v154
	v_add_f32_e32 v155, 1.0, v155
	v_add_f32_e32 v156, 1.0, v156
	v_add_f32_e32 v157, 1.0, v157
	v_add_f32_e32 v158, 1.0, v158
	v_add_f32_e32 v159, 1.0, v159
	v_rcp_f32_e32 v152, v152
	v_rcp_f32_e32 v153, v153
	v_rcp_f32_e32 v154, v154
	v_rcp_f32_e32 v155, v155
	v_rcp_f32_e32 v156, v156
	v_rcp_f32_e32 v157, v157
	v_rcp_f32_e32 v158, v158
	v_rcp_f32_e32 v159, v159
	v_mul_f32_e32 v152, v30, v152
	v_mul_f32_e32 v153, v31, v153
	v_mul_f32_e32 v154, v32, v154
	v_mul_f32_e32 v155, v33, v155
	v_mul_f32_e32 v156, v22, v156
	v_mul_f32_e32 v157, v23, v157
	v_mul_f32_e32 v158, v24, v158
	v_mul_f32_e32 v159, v25, v159
	v_mul_f32_e32 v152, v152, v26
	v_mul_f32_e32 v153, v153, v27
	v_mul_f32_e32 v154, v154, v28
	v_mul_f32_e32 v155, v155, v29
	v_mul_f32_e32 v156, v156, v18
	v_mul_f32_e32 v157, v157, v19
	v_mul_f32_e32 v158, v158, v20
	v_mul_f32_e32 v159, v159, v21
	v_cvt_pk_bf16_f32 v160, v152, v153
	v_cvt_pk_bf16_f32 v161, v154, v155
	v_cvt_pk_bf16_f32 v162, v156, v157
	v_cvt_pk_bf16_f32 v163, v158, v159
	v_add_u32_e32 v34, 0xa0, v146
	v_mad_i64_i32 v[34:35], s[20:21], v34, s62, v[140:141]
	v_lshl_add_u64 v[22:23], v[34:35], 0, v[114:115]
	global_store_dwordx4 v[22:23], v[160:163], off
	v_mul_f32_e32 v152, 0xbfb8aa3b, v14
	v_mul_f32_e32 v153, 0xbfb8aa3b, v15
	v_mul_f32_e32 v154, 0xbfb8aa3b, v16
	v_mul_f32_e32 v155, 0xbfb8aa3b, v17
	v_mul_f32_e32 v156, 0xbfb8aa3b, v6
	v_mul_f32_e32 v157, 0xbfb8aa3b, v7
	v_mul_f32_e32 v158, 0xbfb8aa3b, v8
	v_mul_f32_e32 v159, 0xbfb8aa3b, v9
	v_exp_f32_e32 v152, v152
	v_exp_f32_e32 v153, v153
	v_exp_f32_e32 v154, v154
	v_exp_f32_e32 v155, v155
	v_exp_f32_e32 v156, v156
	v_exp_f32_e32 v157, v157
	v_exp_f32_e32 v158, v158
	v_exp_f32_e32 v159, v159
	v_add_f32_e32 v152, 1.0, v152
	v_add_f32_e32 v153, 1.0, v153
	v_add_f32_e32 v154, 1.0, v154
	v_add_f32_e32 v155, 1.0, v155
	v_add_f32_e32 v156, 1.0, v156
	v_add_f32_e32 v157, 1.0, v157
	v_add_f32_e32 v158, 1.0, v158
	v_add_f32_e32 v159, 1.0, v159
	v_rcp_f32_e32 v152, v152
	v_rcp_f32_e32 v153, v153
	v_rcp_f32_e32 v154, v154
	v_rcp_f32_e32 v155, v155
	v_rcp_f32_e32 v156, v156
	v_rcp_f32_e32 v157, v157
	v_rcp_f32_e32 v158, v158
	v_rcp_f32_e32 v159, v159
	v_mul_f32_e32 v152, v14, v152
	v_mul_f32_e32 v153, v15, v153
	v_mul_f32_e32 v154, v16, v154
	v_mul_f32_e32 v155, v17, v155
	v_mul_f32_e32 v156, v6, v156
	v_mul_f32_e32 v157, v7, v157
	v_mul_f32_e32 v158, v8, v158
	v_mul_f32_e32 v159, v9, v159
	v_mul_f32_e32 v152, v152, v10
	v_mul_f32_e32 v153, v153, v11
	v_mul_f32_e32 v154, v154, v12
	v_mul_f32_e32 v155, v155, v13
	v_mul_f32_e32 v156, v156, v2
	v_mul_f32_e32 v157, v157, v3
	v_mul_f32_e32 v158, v158, v4
	v_mul_f32_e32 v159, v159, v5
	v_cvt_pk_bf16_f32 v160, v152, v153
	v_cvt_pk_bf16_f32 v161, v154, v155
	v_cvt_pk_bf16_f32 v162, v156, v157
	v_cvt_pk_bf16_f32 v163, v158, v159
	v_add_u32_e32 v18, 0xb0, v146
	v_mad_i64_i32 v[18:19], s[20:21], v18, s62, v[140:141]
	s_mov_b64 s[20:21], -1
	v_lshl_add_u64 v[6:7], v[18:19], 0, v[114:115]
	global_store_dwordx4 v[6:7], v[160:163], off
	s_cbranch_vccnz .LBB0_940
	s_and_b64 vcc, exec, s[38:39]
	s_cbranch_vccnz .LBB0_939
	s_barrier
	s_branch .LBB0_939

.LBB0_1023:
	s_ashr_i32 s14, s59, 5
	s_mul_hi_i32 s15, s14, 0x9000
	s_mul_i32 s14, s14, 0x9000
	s_add_u32 s14, s46, s14
	s_addc_u32 s15, s47, s15
	v_lshl_add_u32 v200, s60, 8, v158
	v_ashrrev_i32_e32 v201, 31, v200
	v_lshlrev_b64 v[200:201], 2, v[200:201]
	v_lshl_add_u64 v[202:203], s[14:15], 0, v[200:201]
	s_mov_b64 s[14:15], -1
	s_and_b64 vcc, exec, s[40:41]
	global_load_dwordx4 v[136:139], v[202:203], off
	global_load_dwordx4 v[140:143], v[202:203], off offset:64
	global_load_dwordx4 v[144:147], v[202:203], off offset:512
	global_load_dwordx4 v[148:151], v[202:203], off offset:576
	v_lshl_add_u32 v194, s59, 8, v156
	v_mov_b32_e32 v196, v194
	v_ashrrev_i32_e32 v197, 31, v196
	v_lshlrev_b64 v[196:197], 12, v[196:197]
	v_lshl_add_u64 v[196:197], v[196:197], 0, v[200:201]
	v_lshl_add_u64 v[198:199], s[48:49], 0, v[196:197]
	global_load_dwordx4 v[152:155], v[198:199], off
	global_load_dwordx4 v[160:163], v[198:199], off offset:64
	global_load_dwordx4 v[164:167], v[198:199], off offset:512
	global_load_dwordx4 v[168:171], v[198:199], off offset:576
	v_add_u32_e32 v196, 16, v194
	v_ashrrev_i32_e32 v197, 31, v196
	v_lshlrev_b64 v[196:197], 12, v[196:197]
	v_lshl_add_u64 v[196:197], v[196:197], 0, v[200:201]
	v_lshl_add_u64 v[198:199], s[48:49], 0, v[196:197]
	global_load_dwordx4 v[172:175], v[198:199], off
	global_load_dwordx4 v[176:179], v[198:199], off offset:64
	global_load_dwordx4 v[180:183], v[198:199], off offset:512
	global_load_dwordx4 v[184:187], v[198:199], off offset:576
	s_waitcnt vmcnt(4)
	v_pk_mul_f32 v[136:137], v[136:137], 0.5 op_sel_hi:[1,0]
	v_pk_mul_f32 v[138:139], v[138:139], 0.5 op_sel_hi:[1,0]
	v_pk_mul_f32 v[140:141], v[140:141], 0.5 op_sel_hi:[1,0]
	v_pk_mul_f32 v[142:143], v[142:143], 0.5 op_sel_hi:[1,0]
	v_pk_mul_f32 v[144:145], v[144:145], 0.5 op_sel_hi:[1,0]
	v_pk_mul_f32 v[146:147], v[146:147], 0.5 op_sel_hi:[1,0]
	v_pk_mul_f32 v[148:149], v[148:149], 0.5 op_sel_hi:[1,0]
	v_pk_mul_f32 v[150:151], v[150:151], 0.5 op_sel_hi:[1,0]
	v_pk_fma_f32 v[126:127], v[126:127], v[136:137], v[152:153]
	v_pk_fma_f32 v[128:129], v[128:129], v[138:139], v[154:155]
	v_pk_fma_f32 v[122:123], v[122:123], v[140:141], v[160:161]
	v_pk_fma_f32 v[124:125], v[124:125], v[142:143], v[162:163]
	v_pk_fma_f32 v[118:119], v[118:119], v[144:145], v[164:165]
	v_pk_fma_f32 v[120:121], v[120:121], v[146:147], v[166:167]
	v_pk_fma_f32 v[114:115], v[114:115], v[148:149], v[168:169]
	v_pk_fma_f32 v[116:117], v[116:117], v[150:151], v[170:171]
	v_mov_b32_e32 v196, v194
	v_ashrrev_i32_e32 v197, 31, v196
	v_lshlrev_b64 v[196:197], 12, v[196:197]
	v_lshl_add_u64 v[196:197], v[196:197], 0, v[200:201]
	v_lshl_add_u64 v[192:193], s[48:49], 0, v[196:197]
	global_store_dwordx4 v[192:193], v[126:129], off
	global_store_dwordx4 v[192:193], v[122:125], off offset:64
	global_store_dwordx4 v[192:193], v[118:121], off offset:512
	global_store_dwordx4 v[192:193], v[114:117], off offset:576
	s_nop 1
	v_add_u32_e32 v196, 32, v194
	v_ashrrev_i32_e32 v197, 31, v196
	v_lshlrev_b64 v[196:197], 12, v[196:197]
	v_lshl_add_u64 v[196:197], v[196:197], 0, v[200:201]
	v_lshl_add_u64 v[198:199], s[48:49], 0, v[196:197]
	global_load_dwordx4 v[188:191], v[198:199], off
	global_load_dwordx4 v[152:155], v[198:199], off offset:64
	global_load_dwordx4 v[160:163], v[198:199], off offset:512
	global_load_dwordx4 v[164:167], v[198:199], off offset:576
	v_add_u32_e32 v196, 48, v194
	v_ashrrev_i32_e32 v197, 31, v196
	v_lshlrev_b64 v[196:197], 12, v[196:197]
	v_lshl_add_u64 v[196:197], v[196:197], 0, v[200:201]
	v_lshl_add_u64 v[198:199], s[48:49], 0, v[196:197]
	global_load_dwordx4 v[168:171], v[198:199], off
	global_load_dwordx4 v[126:129], v[198:199], off offset:64
	global_load_dwordx4 v[122:125], v[198:199], off offset:512
	global_load_dwordx4 v[118:121], v[198:199], off offset:576
	s_waitcnt vmcnt(12)
	v_pk_fma_f32 v[110:111], v[110:111], v[136:137], v[172:173]
	v_pk_fma_f32 v[112:113], v[112:113], v[138:139], v[174:175]
	v_pk_fma_f32 v[106:107], v[106:107], v[140:141], v[176:177]
	v_pk_fma_f32 v[108:109], v[108:109], v[142:143], v[178:179]
	v_pk_fma_f32 v[102:103], v[102:103], v[144:145], v[180:181]
	v_pk_fma_f32 v[104:105], v[104:105], v[146:147], v[182:183]
	v_pk_fma_f32 v[98:99], v[98:99], v[148:149], v[184:185]
	v_pk_fma_f32 v[100:101], v[100:101], v[150:151], v[186:187]
	v_add_u32_e32 v196, 16, v194
	v_ashrrev_i32_e32 v197, 31, v196
	v_lshlrev_b64 v[196:197], 12, v[196:197]
	v_lshl_add_u64 v[196:197], v[196:197], 0, v[200:201]
	v_lshl_add_u64 v[192:193], s[48:49], 0, v[196:197]
	global_store_dwordx4 v[192:193], v[110:113], off
	global_store_dwordx4 v[192:193], v[106:109], off offset:64
	global_store_dwordx4 v[192:193], v[102:105], off offset:512
	global_store_dwordx4 v[192:193], v[98:101], off offset:576
	s_nop 1
	v_add_u32_e32 v196, 0x80, v194
	v_ashrrev_i32_e32 v197, 31, v196
	v_lshlrev_b64 v[196:197], 12, v[196:197]
	v_lshl_add_u64 v[196:197], v[196:197], 0, v[200:201]
	v_lshl_add_u64 v[198:199], s[48:49], 0, v[196:197]
	global_load_dwordx4 v[114:117], v[198:199], off
	global_load_dwordx4 v[172:175], v[198:199], off offset:64
	global_load_dwordx4 v[176:179], v[198:199], off offset:512
	global_load_dwordx4 v[180:183], v[198:199], off offset:576
	v_add_u32_e32 v196, 0x90, v194
	v_ashrrev_i32_e32 v197, 31, v196
	v_lshlrev_b64 v[196:197], 12, v[196:197]
	v_lshl_add_u64 v[196:197], v[196:197], 0, v[200:201]
	v_lshl_add_u64 v[198:199], s[48:49], 0, v[196:197]
	global_load_dwordx4 v[184:187], v[198:199], off
	global_load_dwordx4 v[110:113], v[198:199], off offset:64
	global_load_dwordx4 v[106:109], v[198:199], off offset:512
	global_load_dwordx4 v[102:105], v[198:199], off offset:576
	s_waitcnt vmcnt(16)
	v_pk_fma_f32 v[94:95], v[94:95], v[136:137], v[188:189]
	v_pk_fma_f32 v[96:97], v[96:97], v[138:139], v[190:191]
	v_pk_fma_f32 v[90:91], v[90:91], v[140:141], v[152:153]
	v_pk_fma_f32 v[92:93], v[92:93], v[142:143], v[154:155]
	v_pk_fma_f32 v[86:87], v[86:87], v[144:145], v[160:161]
	v_pk_fma_f32 v[88:89], v[88:89], v[146:147], v[162:163]
	v_pk_fma_f32 v[82:83], v[82:83], v[148:149], v[164:165]
	v_pk_fma_f32 v[84:85], v[84:85], v[150:151], v[166:167]
	v_add_u32_e32 v196, 32, v194
	v_ashrrev_i32_e32 v197, 31, v196
	v_lshlrev_b64 v[196:197], 12, v[196:197]
	v_lshl_add_u64 v[196:197], v[196:197], 0, v[200:201]
	v_lshl_add_u64 v[192:193], s[48:49], 0, v[196:197]
	global_store_dwordx4 v[192:193], v[94:97], off
	global_store_dwordx4 v[192:193], v[90:93], off offset:64
	global_store_dwordx4 v[192:193], v[86:89], off offset:512
	global_store_dwordx4 v[192:193], v[82:85], off offset:576
	s_nop 1
	v_add_u32_e32 v196, 0xa0, v194
	v_ashrrev_i32_e32 v197, 31, v196
	v_lshlrev_b64 v[196:197], 12, v[196:197]
	v_lshl_add_u64 v[196:197], v[196:197], 0, v[200:201]
	v_lshl_add_u64 v[198:199], s[48:49], 0, v[196:197]
	global_load_dwordx4 v[98:101], v[198:199], off
	global_load_dwordx4 v[188:191], v[198:199], off offset:64
	global_load_dwordx4 v[152:155], v[198:199], off offset:512
	global_load_dwordx4 v[160:163], v[198:199], off offset:576
	v_add_u32_e32 v196, 0xb0, v194
	v_ashrrev_i32_e32 v197, 31, v196
	v_lshlrev_b64 v[196:197], 12, v[196:197]
	v_lshl_add_u64 v[196:197], v[196:197], 0, v[200:201]
	v_lshl_add_u64 v[198:199], s[48:49], 0, v[196:197]
	global_load_dwordx4 v[164:167], v[198:199], off
	global_load_dwordx4 v[94:97], v[198:199], off offset:64
	global_load_dwordx4 v[90:93], v[198:199], off offset:512
	global_load_dwordx4 v[86:89], v[198:199], off offset:576
	s_waitcnt vmcnt(24)
	v_pk_fma_f32 v[78:79], v[78:79], v[136:137], v[168:169]
	v_pk_fma_f32 v[80:81], v[80:81], v[138:139], v[170:171]
	v_pk_fma_f32 v[74:75], v[74:75], v[140:141], v[126:127]
	v_pk_fma_f32 v[76:77], v[76:77], v[142:143], v[128:129]
	v_pk_fma_f32 v[70:71], v[70:71], v[144:145], v[122:123]
	v_pk_fma_f32 v[72:73], v[72:73], v[146:147], v[124:125]
	v_pk_fma_f32 v[66:67], v[66:67], v[148:149], v[118:119]
	v_pk_fma_f32 v[68:69], v[68:69], v[150:151], v[120:121]
	v_add_u32_e32 v196, 48, v194
	v_ashrrev_i32_e32 v197, 31, v196
	v_lshlrev_b64 v[196:197], 12, v[196:197]
	v_lshl_add_u64 v[196:197], v[196:197], 0, v[200:201]
	v_lshl_add_u64 v[192:193], s[48:49], 0, v[196:197]
	global_store_dwordx4 v[192:193], v[78:81], off
	global_store_dwordx4 v[192:193], v[74:77], off offset:64
	global_store_dwordx4 v[192:193], v[70:73], off offset:512
	global_store_dwordx4 v[192:193], v[66:69], off offset:576
	s_waitcnt vmcnt(20)
	v_pk_fma_f32 v[62:63], v[62:63], v[136:137], v[114:115]
	v_pk_fma_f32 v[64:65], v[64:65], v[138:139], v[116:117]
	v_pk_fma_f32 v[58:59], v[58:59], v[140:141], v[172:173]
	v_pk_fma_f32 v[60:61], v[60:61], v[142:143], v[174:175]
	v_pk_fma_f32 v[54:55], v[54:55], v[144:145], v[176:177]
	v_pk_fma_f32 v[56:57], v[56:57], v[146:147], v[178:179]
	v_pk_fma_f32 v[50:51], v[50:51], v[148:149], v[180:181]
	v_pk_fma_f32 v[52:53], v[52:53], v[150:151], v[182:183]
	v_add_u32_e32 v196, 0x80, v194
	v_ashrrev_i32_e32 v197, 31, v196
	v_lshlrev_b64 v[196:197], 12, v[196:197]
	v_lshl_add_u64 v[196:197], v[196:197], 0, v[200:201]
	v_lshl_add_u64 v[192:193], s[48:49], 0, v[196:197]
	global_store_dwordx4 v[192:193], v[62:65], off
	global_store_dwordx4 v[192:193], v[58:61], off offset:64
	global_store_dwordx4 v[192:193], v[54:57], off offset:512
	global_store_dwordx4 v[192:193], v[50:53], off offset:576
	s_waitcnt vmcnt(20)
	v_pk_fma_f32 v[46:47], v[46:47], v[136:137], v[184:185]
	v_pk_fma_f32 v[48:49], v[48:49], v[138:139], v[186:187]
	v_pk_fma_f32 v[42:43], v[42:43], v[140:141], v[110:111]
	v_pk_fma_f32 v[44:45], v[44:45], v[142:143], v[112:113]
	v_pk_fma_f32 v[38:39], v[38:39], v[144:145], v[106:107]
	v_pk_fma_f32 v[40:41], v[40:41], v[146:147], v[108:109]
	v_pk_fma_f32 v[34:35], v[34:35], v[148:149], v[102:103]
	v_pk_fma_f32 v[36:37], v[36:37], v[150:151], v[104:105]
	v_add_u32_e32 v196, 0x90, v194
	v_ashrrev_i32_e32 v197, 31, v196
	v_lshlrev_b64 v[196:197], 12, v[196:197]
	v_lshl_add_u64 v[196:197], v[196:197], 0, v[200:201]
	v_lshl_add_u64 v[192:193], s[48:49], 0, v[196:197]
	global_store_dwordx4 v[192:193], v[46:49], off
	global_store_dwordx4 v[192:193], v[42:45], off offset:64
	global_store_dwordx4 v[192:193], v[38:41], off offset:512
	global_store_dwordx4 v[192:193], v[34:37], off offset:576
	s_waitcnt vmcnt(16)
	v_pk_fma_f32 v[30:31], v[30:31], v[136:137], v[98:99]
	v_pk_fma_f32 v[32:33], v[32:33], v[138:139], v[100:101]
	v_pk_fma_f32 v[26:27], v[26:27], v[140:141], v[188:189]
	v_pk_fma_f32 v[28:29], v[28:29], v[142:143], v[190:191]
	v_pk_fma_f32 v[22:23], v[22:23], v[144:145], v[152:153]
	v_pk_fma_f32 v[24:25], v[24:25], v[146:147], v[154:155]
	v_pk_fma_f32 v[18:19], v[18:19], v[148:149], v[160:161]
	v_pk_fma_f32 v[20:21], v[20:21], v[150:151], v[162:163]
	v_add_u32_e32 v196, 0xa0, v194
	v_ashrrev_i32_e32 v197, 31, v196
	v_lshlrev_b64 v[196:197], 12, v[196:197]
	v_lshl_add_u64 v[196:197], v[196:197], 0, v[200:201]
	v_lshl_add_u64 v[192:193], s[48:49], 0, v[196:197]
	global_store_dwordx4 v[192:193], v[30:33], off
	global_store_dwordx4 v[192:193], v[26:29], off offset:64
	global_store_dwordx4 v[192:193], v[22:25], off offset:512
	global_store_dwordx4 v[192:193], v[18:21], off offset:576
	s_waitcnt vmcnt(16)
	v_pk_fma_f32 v[14:15], v[14:15], v[136:137], v[164:165]
	v_pk_fma_f32 v[16:17], v[16:17], v[138:139], v[166:167]
	v_pk_fma_f32 v[10:11], v[10:11], v[140:141], v[94:95]
	v_pk_fma_f32 v[12:13], v[12:13], v[142:143], v[96:97]
	v_pk_fma_f32 v[6:7], v[6:7], v[144:145], v[90:91]
	v_pk_fma_f32 v[8:9], v[8:9], v[146:147], v[92:93]
	v_pk_fma_f32 v[2:3], v[2:3], v[148:149], v[86:87]
	v_pk_fma_f32 v[4:5], v[4:5], v[150:151], v[88:89]
	v_add_u32_e32 v196, 0xb0, v194
	v_ashrrev_i32_e32 v197, 31, v196
	v_lshlrev_b64 v[196:197], 12, v[196:197]
	v_lshl_add_u64 v[196:197], v[196:197], 0, v[200:201]
	v_lshl_add_u64 v[192:193], s[48:49], 0, v[196:197]
	global_store_dwordx4 v[192:193], v[14:17], off
	global_store_dwordx4 v[192:193], v[10:13], off offset:64
	global_store_dwordx4 v[192:193], v[6:9], off offset:512
	global_store_dwordx4 v[192:193], v[2:5], off offset:576
	s_cbranch_vccnz .LBB0_1012
	s_and_b64 vcc, exec, s[38:39]
	s_cbranch_vccnz .LBB0_1011
	s_barrier
	s_branch .LBB0_1011

	.amdhsa_kernel _Z10hybrid_fwd4Args
		.amdhsa_group_segment_fixed_size 0
		.amdhsa_private_segment_fixed_size 0
		.amdhsa_kernarg_size 416
		.amdhsa_user_sgpr_count 2
		.amdhsa_user_sgpr_dispatch_ptr 0
		.amdhsa_user_sgpr_queue_ptr 0
		.amdhsa_user_sgpr_kernarg_segment_ptr 1
		.amdhsa_user_sgpr_dispatch_id 0
		.amdhsa_user_sgpr_kernarg_preload_length 0
		.amdhsa_user_sgpr_kernarg_preload_offset 0
		.amdhsa_user_sgpr_private_segment_size 0
		.amdhsa_uses_dynamic_stack 0
		.amdhsa_enable_private_segment 0
		.amdhsa_system_sgpr_workgroup_id_x 1
		.amdhsa_system_sgpr_workgroup_id_y 0
		.amdhsa_system_sgpr_workgroup_id_z 0
		.amdhsa_system_sgpr_workgroup_info 0
		.amdhsa_system_vgpr_workitem_id 2
		.amdhsa_next_free_vgpr 256
		.amdhsa_next_free_sgpr 102
		.amdhsa_accum_offset 256
		.amdhsa_reserve_vcc 1
		.amdhsa_float_round_mode_32 0
		.amdhsa_float_round_mode_16_64 0
		.amdhsa_float_denorm_mode_32 3
		.amdhsa_float_denorm_mode_16_64 3
		.amdhsa_dx10_clamp 1
		.amdhsa_ieee_mode 1
		.amdhsa_fp16_overflow 0
		.amdhsa_tg_split 0
		.amdhsa_exception_fp_ieee_invalid_op 0
		.amdhsa_exception_fp_denorm_src 0
		.amdhsa_exception_fp_ieee_div_zero 0
		.amdhsa_exception_fp_ieee_overflow 0
		.amdhsa_exception_fp_ieee_underflow 0
		.amdhsa_exception_fp_ieee_inexact 0
		.amdhsa_exception_int_div_zero 0
	.end_amdhsa_kernel

amdhsa.kernels:
  - .agpr_count:     0
    .args:
      - .offset:         0
        .size:           160
        .value_kind:     by_value
      - .offset:         160
        .size:           4
        .value_kind:     hidden_block_count_x
      - .offset:         164
        .size:           4
        .value_kind:     hidden_block_count_y
      - .offset:         168
        .size:           4
        .value_kind:     hidden_block_count_z
      - .offset:         172
        .size:           2
        .value_kind:     hidden_group_size_x
      - .offset:         174
        .size:           2
        .value_kind:     hidden_group_size_y
      - .offset:         176
        .size:           2
        .value_kind:     hidden_group_size_z
      - .offset:         178
        .size:           2
        .value_kind:     hidden_remainder_x
      - .offset:         180
        .size:           2
        .value_kind:     hidden_remainder_y
      - .offset:         182
        .size:           2
        .value_kind:     hidden_remainder_z
      - .offset:         200
        .size:           8
        .value_kind:     hidden_global_offset_x
      - .offset:         208
        .size:           8
        .value_kind:     hidden_global_offset_y
      - .offset:         216
        .size:           8
        .value_kind:     hidden_global_offset_z
      - .offset:         224
        .size:           2
        .value_kind:     hidden_grid_dims
      - .offset:         248
        .size:           8
        .value_kind:     hidden_multigrid_sync_arg
      - .offset:         280
        .size:           4
        .value_kind:     hidden_dynamic_lds_size
    .group_segment_fixed_size: 0
    .kernarg_segment_align: 8
    .kernarg_segment_size: 416
    .language:       OpenCL C
    .language_version:
      - 2
      - 0
    .max_flat_workgroup_size: 512
    .name:           _Z10hybrid_fwd4Args
    .private_segment_fixed_size: 0
    .sgpr_count:     108
    .sgpr_spill_count: 168
    .symbol:         _Z10hybrid_fwd4Args.kd
    .uniform_work_group_size: 1
    .uses_dynamic_stack: false
    .vgpr_count:     256
    .vgpr_spill_count: 0
    .wavefront_size: 64
